# offset-restoring barrier of the trailing half moved after the unit scheduler in 7 more GEMM instances (down, in-proj, out-proj, UQ/UKV)
# speedup vs baseline: 1.0181x; 1.0060x over previous
; #define PG8_STAGE(bufoff, gbase, voff) do { _Pragma("unroll") for (int _i = 0; _i < 2; ++_i) \
;         __builtin_amdgcn_global_load_lds((const unsigned*)((const char*)(gbase) + (voff)[_i]), (PG8_LAS unsigned*)(lds + (bufoff) + ldsw + _i * 8192), 16, 0, 0); } while (0)
; #define PG8_WAIT_V(n) asm volatile("s_waitcnt vmcnt(" #n ")" ::: "memory")
; #define PG8_BAR __builtin_amdgcn_s_barrier()
;     __device__ __forceinline__ void operator()(const f32x4 (&acc)[2][2][4][2], const Unit& u, int wr, int wc, int fr, int fq) const {
;         float* wl = wlds + (wr * 4 + wc) * 576;
;         const int lane = fq * 16 + fr, rl = lane >> 3, ch = lane & 7;
;         f32x4 rb[2][2][2][2];
;         const size_t cbase = (size_t)u.pn * BM + wc * 32 + ch * 4;
; template <class Epi, class Sched, bool ALIGN_EPI = false, bool SP2 = false>
; __device__ __forceinline__ void gemm_phase(PG8_LAS unsigned char* lds, const Gemm g, const Sched& S, const Epi& E) {
;     ...
;         PG8_WAIT_V(2); PG8_BAR;
;         PG8_STAGE(PG8_SB(1, 0), cB + kstep, voffB); PG8_STAGE(PG8_SA(1, 0), cA + kstep, voffA); PG8_STAGE(PG8_SB(1, 1), cB + hstep + kstep, voffB);
;         PG8_WAIT_V(6); PG8_BAR;
.LBB0_301:
	s_add_i32 m0, s8, 0x18000
	v_lshl_add_u64 v[0:1], v[0:1], 0, s[20:21]
	s_waitcnt vmcnt(2)
	s_barrier
	global_load_lds_dwordx4 v[0:1], off
	v_lshl_add_u64 v[0:1], v[2:3], 0, s[20:21]
	s_add_i32 m0, s8, 0x1a000
	s_add_i32 s48, s8, 0x8000
	global_load_lds_dwordx4 v[0:1], off
	v_lshl_add_u64 v[0:1], v[8:9], 0, s[20:21]
	s_mov_b32 m0, s48
	s_add_i32 s64, s8, 0xa000
	global_load_lds_dwordx4 v[0:1], off
	v_lshl_add_u64 v[0:1], v[10:11], 0, s[20:21]
	s_mov_b32 m0, s64
	s_lshr_b32 s1, s1, 26
	global_load_lds_dwordx4 v[0:1], off
	s_add_i32 m0, s8, 0x1c000
	v_lshl_add_u64 v[0:1], v[4:5], 0, s[20:21]
	global_load_lds_dwordx4 v[0:1], off
	v_lshl_add_u64 v[0:1], v[6:7], 0, s[20:21]
	s_add_i32 m0, s8, 0x1e000
	v_and_b32_e32 v13, 15, v12
	global_load_lds_dwordx4 v[0:1], off
	s_add_i32 s1, s0, s1
	v_and_b32_e32 v14, 48, v12
	v_lshlrev_b32_e32 v16, 2, v12
	s_and_b32 s40, s37, 3
	s_ashr_i32 s37, s1, 6
	v_lshl_or_b32 v15, v13, 6, v14
	s_lshl_b32 s1, s39, 13
	v_and_b32_e32 v16, 32, v16
	v_bitop3_b32 v17, v15, s1, v16 bitop3:0xde
	s_lshl_b32 s1, s40, 12
	s_cmp_gt_i32 s0, 63
	s_cselect_b64 s[56:57], -1, 0
	s_add_i32 s65, s37, -2
	s_cmpk_lt_u32 s38, 0x100
	v_and_b32_e32 v1, 7, v12
	s_cselect_b64 s[58:59], -1, 0
	s_lshl_b32 s0, s39, 2
	v_lshlrev_b32_e32 v2, 2, v1
	v_bitop3_b32 v131, v15, s1, v16 bitop3:0xde
	s_or_b32 s0, s0, s40
	v_lshl_or_b32 v130, s40, 5, v2
	s_ashr_i32 s45, s44, 31
	s_lshl_b32 s1, s40, 2
	v_readlane_b32 s40, v252, 38
	v_bfe_u32 v0, v12, 3, 3
	v_readlane_b32 s41, v252, 39
	s_add_u32 s67, s40, s1
	s_mulk_i32 s0, 0x900
	v_lshl_or_b32 v196, s39, 6, v0
	v_mul_u32_u24_e32 v0, 36, v0
	s_addc_u32 s68, s41, 0
	s_lshl_b32 s70, s29, 3
	s_add_i32 s0, s0, 0
	v_cmp_eq_u32_e64 s[38:39], 0, v1
	s_add_i32 s0, s0, 0x20000
	v_lshlrev_b32_e32 v1, 4, v1
	v_lshlrev_b32_e32 v0, 2, v0
	s_abs_i32 s72, s70
	v_add3_u32 v198, s0, v1, v0
	v_cvt_f32_u32_e32 v0, s72
	v_mul_u32_u24_e32 v2, 36, v13
	v_lshlrev_b32_e32 v2, 2, v2
	v_add3_u32 v197, s0, v2, v14
	v_rcp_iflag_f32_e32 v0, v0
	s_sub_i32 s0, 0, s72
	s_waitcnt vmcnt(6)
	s_mov_b32 s66, 0
	v_mul_f32_e32 v0, 0x4f7ffffe, v0
	v_cvt_u32_f32_e32 v0, v0
	s_lshl_b32 s69, s29, 4
	v_mov_b32_e32 v132, v192
	v_mov_b32_e32 v133, v192
	v_readfirstlane_b32 s1, v0
	s_mul_i32 s0, s0, s1
	s_mul_hi_u32 s0, s1, s0
	s_bfe_i32 s71, s29, 0x1001c
	s_add_i32 s73, s1, s0
	v_lshl_add_u64 v[134:135], s[50:51], 0, v[208:209]
	v_lshl_add_u64 v[136:137], s[50:51], 0, v[128:129]
	v_add_u32_e32 v199, 0, v17
	s_barrier
	s_mov_b32 s96, 0
	s_branch .LBB0_304

; #define PG8_BAR __builtin_amdgcn_s_barrier()
; template <class Epi, class Sched, bool ALIGN_EPI = false, bool SP2 = false>
; __device__ __forceinline__ void gemm_phase(PG8_LAS unsigned char* lds, const Gemm g, const Sched& S, const Epi& E) {
;     ...
;                     for (int n = 0; n < 2; ++n) acc[a][b][m][n] = (f32x4){0.f, 0.f, 0.f, 0.f};
;         cur = nxt; cA = nA; cB = nB; ++ui;
;         if constexpr (ALIGN_EPI) { if (wr == 1) PG8_BAR; }
.LBB0_310:
	s_cmp_eq_u32 s96, 1
	s_cbranch_scc0 .Lno_restore_bar_0
	s_barrier

; #define PG8_BAR __builtin_amdgcn_s_barrier()
; template <class Epi, class Sched, bool ALIGN_EPI = false, bool SP2 = false>
; __device__ __forceinline__ void gemm_phase(PG8_LAS unsigned char* lds, const Gemm g, const Sched& S, const Epi& E) {
;     ...
;         if constexpr (!Epi::AFTER_DRAIN) { E(acc, cur, wr, wc, fr, fq); S.done(cur); }
;         if (!has_next) break;
; #pragma unroll
;         for (int a = 0; a < 2; ++a)
; #pragma unroll
;             for (int b = 0; b < 2; ++b)
; #pragma unroll
;                 for (int m = 0; m < 4; ++m)
; #pragma unroll
;                     for (int n = 0; n < 2; ++n) acc[a][b][m][n] = (f32x4){0.f, 0.f, 0.f, 0.f};
;         cur = nxt; cA = nA; cB = nB; ++ui;
;         if constexpr (ALIGN_EPI) { if (wr == 1) PG8_BAR; }
.LBB0_347:
	s_or_b64 exec, exec, s[30:31]
	s_and_b64 vcc, exec, s[40:41]
	s_mov_b64 s[28:29], -1
	s_cbranch_vccnz .LBB0_303
	s_mov_b32 s96, 0
	s_andn2_b64 vcc, exec, s[54:55]
	s_cbranch_vccnz .LBB0_302
	s_mov_b32 s96, 1
	s_branch .LBB0_302

; #define PG8_STAGE(bufoff, gbase, voff) do { _Pragma("unroll") for (int _i = 0; _i < 2; ++_i) \
;         __builtin_amdgcn_global_load_lds((const unsigned*)((const char*)(gbase) + (voff)[_i]), (PG8_LAS unsigned*)(lds + (bufoff) + ldsw + _i * 8192), 16, 0, 0); } while (0)
; #define PG8_WAIT_V(n) asm volatile("s_waitcnt vmcnt(" #n ")" ::: "memory")
; #define PG8_BAR __builtin_amdgcn_s_barrier()
;     __device__ __forceinline__ void operator()(const f32x4 (&acc)[2][2][4][2], const Unit& u, int wr, int wc, int fr, int fq) const {
;         float* wl = wlds + (wr * 4 + wc) * 576;
;         const int lane = fq * 16 + fr, rl = lane >> 3, ch = lane & 7;
;         f32x4 rb[2][2][2][2];
;         const size_t cbase = (size_t)u.pn * BM + wc * 32 + ch * 4;
; template <class Epi, class Sched, bool ALIGN_EPI = false, bool SP2 = false>
; __device__ __forceinline__ void gemm_phase(PG8_LAS unsigned char* lds, const Gemm g, const Sched& S, const Epi& E) {
;     ...
;         PG8_WAIT_V(2); PG8_BAR;
;         PG8_STAGE(PG8_SB(1, 0), cB + kstep, voffB); PG8_STAGE(PG8_SA(1, 0), cA + kstep, voffA); PG8_STAGE(PG8_SB(1, 1), cB + hstep + kstep, voffB);
;         PG8_WAIT_V(6); PG8_BAR;
.LBB0_358:
	s_add_i32 m0, s8, 0x18000
	v_lshl_add_u64 v[0:1], v[0:1], 0, s[20:21]
	s_waitcnt vmcnt(2)
	s_barrier
	global_load_lds_dwordx4 v[0:1], off
	v_lshl_add_u64 v[0:1], v[2:3], 0, s[20:21]
	s_add_i32 m0, s8, 0x1a000
	s_add_i32 s48, s8, 0x8000
	global_load_lds_dwordx4 v[0:1], off
	v_lshl_add_u64 v[0:1], v[8:9], 0, s[20:21]
	s_mov_b32 m0, s48
	s_add_i32 s49, s8, 0xa000
	global_load_lds_dwordx4 v[0:1], off
	v_lshl_add_u64 v[0:1], v[10:11], 0, s[20:21]
	s_mov_b32 m0, s49
	s_lshr_b32 s1, s1, 26
	global_load_lds_dwordx4 v[0:1], off
	s_add_i32 m0, s8, 0x1c000
	v_lshl_add_u64 v[0:1], v[4:5], 0, s[20:21]
	global_load_lds_dwordx4 v[0:1], off
	v_lshl_add_u64 v[0:1], v[6:7], 0, s[20:21]
	s_add_i32 m0, s8, 0x1e000
	v_and_b32_e32 v13, 15, v12
	global_load_lds_dwordx4 v[0:1], off
	s_add_i32 s1, s0, s1
	v_and_b32_e32 v14, 48, v12
	v_lshlrev_b32_e32 v16, 2, v12
	s_and_b32 s40, s37, 3
	s_ashr_i32 s79, s1, 6
	v_lshl_or_b32 v15, v13, 6, v14
	s_lshl_b32 s1, s39, 13
	v_and_b32_e32 v16, 32, v16
	v_bitop3_b32 v17, v15, s1, v16 bitop3:0xde
	s_lshl_b32 s1, s40, 12
	s_cmp_gt_i32 s0, 63
	s_cselect_b64 s[16:17], -1, 0
	s_add_i32 s37, s79, -2
	s_cmpk_lt_u32 s38, 0x100
	v_and_b32_e32 v1, 7, v12
	s_cselect_b64 s[46:47], -1, 0
	s_lshl_b32 s0, s39, 2
	v_lshlrev_b32_e32 v2, 2, v1
	v_bitop3_b32 v197, v15, s1, v16 bitop3:0xde
	s_or_b32 s0, s0, s40
	v_lshl_or_b32 v196, s40, 5, v2
	s_ashr_i32 s45, s44, 31
	s_lshl_b32 s1, s40, 2
	v_readlane_b32 s40, v252, 38
	v_bfe_u32 v0, v12, 3, 3
	v_readlane_b32 s41, v252, 39
	s_add_u32 s95, s40, s1
	s_mulk_i32 s0, 0x900
	v_lshl_or_b32 v211, s39, 6, v0
	v_mul_u32_u24_e32 v0, 36, v0
	s_addc_u32 s68, s41, 0
	s_lshl_b32 s70, s29, 3
	s_add_i32 s0, s0, 0
	v_cmp_eq_u32_e64 s[38:39], 0, v1
	s_add_i32 s0, s0, 0x20000
	v_lshlrev_b32_e32 v1, 4, v1
	v_lshlrev_b32_e32 v0, 2, v0
	s_abs_i32 s72, s70
	v_add3_u32 v229, s0, v1, v0
	v_cvt_f32_u32_e32 v0, s72
	v_mul_u32_u24_e32 v2, 36, v13
	v_lshlrev_b32_e32 v2, 2, v2
	v_add3_u32 v228, s0, v2, v14
	v_rcp_iflag_f32_e32 v0, v0
	s_sub_i32 s0, 0, s72
	s_waitcnt vmcnt(6)
	s_mov_b32 s94, 0
	v_mul_f32_e32 v0, 0x4f7ffffe, v0
	v_cvt_u32_f32_e32 v0, v0
	s_lshl_b32 s69, s29, 4
	v_mov_b32_e32 v198, v192
	v_mov_b32_e32 v199, v192
	v_readfirstlane_b32 s1, v0
	s_mul_i32 s0, s0, s1
	s_mul_hi_u32 s0, s1, s0
	s_bfe_i32 s71, s29, 0x1001c
	s_add_i32 s73, s1, s0
	v_lshl_add_u64 v[200:201], s[50:51], 0, v[208:209]
	v_lshl_add_u64 v[202:203], s[50:51], 0, v[194:195]
	v_add_u32_e32 v230, 0, v17
	s_barrier
	s_mov_b32 s96, 0
	s_branch .LBB0_361

; #define PG8_BAR __builtin_amdgcn_s_barrier()
; template <class Epi, class Sched, bool ALIGN_EPI = false, bool SP2 = false>
; __device__ __forceinline__ void gemm_phase(PG8_LAS unsigned char* lds, const Gemm g, const Sched& S, const Epi& E) {
;     ...
;     for (;;) {
;         const bool has_next = S.next(ui + 1, nxt);
;         const char* nA = has_next ? (const char*)g.A + (size_t)nxt.pm * tstep : cA; const char* nB = has_next ? (const char*)g.Bt + (size_t)nxt.pn * tstep : cB;
;         for (int t = 0; t < nt; t += 2) {
;     ...
;                     for (int n = 0; n < 2; ++n) acc[a][b][m][n] = (f32x4){0.f, 0.f, 0.f, 0.f};
;         cur = nxt; cA = nA; cB = nB; ++ui;
;         if constexpr (ALIGN_EPI) { if (wr == 1) PG8_BAR; }
.LBB0_367:
	s_waitcnt vmcnt(0)
	s_cmp_eq_u32 s96, 1
	s_cbranch_scc0 .Lno_restore_bar_1
	s_barrier
.Lno_restore_bar_1:
	s_andn2_b64 vcc, exec, s[16:17]
	s_cbranch_vccz .Lpeel_k3
	v_mov_b32_e32 v127, 0
	v_mov_b32_e32 v126, v127
	v_mov_b32_e32 v125, v127
	v_mov_b32_e32 v124, v127
	v_mov_b32_e32 v123, v127
	v_mov_b32_e32 v122, v127
	v_mov_b32_e32 v121, v127
	v_mov_b32_e32 v120, v127
	v_mov_b32_e32 v111, v127
	v_mov_b32_e32 v110, v127
	v_mov_b32_e32 v109, v127
	v_mov_b32_e32 v108, v127
	v_mov_b32_e32 v107, v127
	v_mov_b32_e32 v106, v127
	v_mov_b32_e32 v105, v127
	v_mov_b32_e32 v104, v127
	v_mov_b32_e32 v95, v127
	v_mov_b32_e32 v94, v127
	v_mov_b32_e32 v93, v127
	v_mov_b32_e32 v92, v127
	v_mov_b32_e32 v91, v127
	v_mov_b32_e32 v90, v127
	v_mov_b32_e32 v89, v127
	v_mov_b32_e32 v88, v127
	v_mov_b32_e32 v79, v127
	v_mov_b32_e32 v78, v127
	v_mov_b32_e32 v77, v127
	v_mov_b32_e32 v76, v127
	v_mov_b32_e32 v75, v127
	v_mov_b32_e32 v74, v127
	v_mov_b32_e32 v73, v127
	v_mov_b32_e32 v72, v127
	v_mov_b32_e32 v119, v127
	v_mov_b32_e32 v118, v127
	v_mov_b32_e32 v117, v127
	v_mov_b32_e32 v116, v127
	v_mov_b32_e32 v115, v127
	v_mov_b32_e32 v114, v127
	v_mov_b32_e32 v113, v127
	v_mov_b32_e32 v112, v127
	v_mov_b32_e32 v103, v127
	v_mov_b32_e32 v102, v127
	v_mov_b32_e32 v101, v127
	v_mov_b32_e32 v100, v127
	v_mov_b32_e32 v99, v127
	v_mov_b32_e32 v98, v127
	v_mov_b32_e32 v97, v127
	v_mov_b32_e32 v96, v127
	v_mov_b32_e32 v87, v127
	v_mov_b32_e32 v86, v127
	v_mov_b32_e32 v85, v127
	v_mov_b32_e32 v84, v127
	v_mov_b32_e32 v83, v127
	v_mov_b32_e32 v82, v127
	v_mov_b32_e32 v81, v127
	v_mov_b32_e32 v80, v127
	v_mov_b32_e32 v71, v127
	v_mov_b32_e32 v70, v127
	v_mov_b32_e32 v69, v127
	v_mov_b32_e32 v68, v127
	v_mov_b32_e32 v67, v127
	v_mov_b32_e32 v66, v127
	v_mov_b32_e32 v65, v127
	v_mov_b32_e32 v64, v127
	v_mov_b32_e32 v63, v127
	v_mov_b32_e32 v62, v127
	v_mov_b32_e32 v61, v127
	v_mov_b32_e32 v60, v127
	v_mov_b32_e32 v59, v127
	v_mov_b32_e32 v58, v127
	v_mov_b32_e32 v57, v127
	v_mov_b32_e32 v56, v127
	v_mov_b32_e32 v47, v127
	v_mov_b32_e32 v46, v127
	v_mov_b32_e32 v45, v127
	v_mov_b32_e32 v44, v127
	v_mov_b32_e32 v43, v127
	v_mov_b32_e32 v42, v127
	v_mov_b32_e32 v41, v127
	v_mov_b32_e32 v40, v127
	v_mov_b32_e32 v31, v127
	v_mov_b32_e32 v30, v127
	v_mov_b32_e32 v29, v127
	v_mov_b32_e32 v28, v127
	v_mov_b32_e32 v27, v127
	v_mov_b32_e32 v26, v127
	v_mov_b32_e32 v25, v127
	v_mov_b32_e32 v24, v127
	v_mov_b32_e32 v15, v127
	v_mov_b32_e32 v14, v127
	v_mov_b32_e32 v13, v127
	v_mov_b32_e32 v12, v127
	v_mov_b32_e32 v11, v127
	v_mov_b32_e32 v10, v127
	v_mov_b32_e32 v9, v127
	v_mov_b32_e32 v8, v127
	v_mov_b32_e32 v55, v127
	v_mov_b32_e32 v54, v127
	v_mov_b32_e32 v53, v127
	v_mov_b32_e32 v52, v127
	v_mov_b32_e32 v51, v127
	v_mov_b32_e32 v50, v127
	v_mov_b32_e32 v49, v127
	v_mov_b32_e32 v48, v127
	v_mov_b32_e32 v39, v127
	v_mov_b32_e32 v38, v127
	v_mov_b32_e32 v37, v127
	v_mov_b32_e32 v36, v127
	v_mov_b32_e32 v35, v127
	v_mov_b32_e32 v34, v127
	v_mov_b32_e32 v33, v127
	v_mov_b32_e32 v32, v127
	v_mov_b32_e32 v23, v127
	v_mov_b32_e32 v22, v127
	v_mov_b32_e32 v21, v127
	v_mov_b32_e32 v20, v127
	v_mov_b32_e32 v19, v127
	v_mov_b32_e32 v18, v127
	v_mov_b32_e32 v17, v127
	v_mov_b32_e32 v16, v127
	v_mov_b32_e32 v7, v127
	v_mov_b32_e32 v6, v127
	v_mov_b32_e32 v5, v127
	v_mov_b32_e32 v4, v127
	v_mov_b32_e32 v3, v127
	v_mov_b32_e32 v2, v127
	v_mov_b32_e32 v1, v127
	v_mov_b32_e32 v0, v127
	s_branch .LBB0_370

; #define PG8_BAR __builtin_amdgcn_s_barrier()
; template <class Epi, class Sched, bool ALIGN_EPI = false, bool SP2 = false>
; __device__ __forceinline__ void gemm_phase(PG8_LAS unsigned char* lds, const Gemm g, const Sched& S, const Epi& E) {
;     ...
;         if constexpr (!Epi::AFTER_DRAIN) { E(acc, cur, wr, wc, fr, fq); S.done(cur); }
;         if (!has_next) break;
; #pragma unroll
;         for (int a = 0; a < 2; ++a)
; #pragma unroll
;             for (int b = 0; b < 2; ++b)
; #pragma unroll
;                 for (int m = 0; m < 4; ++m)
; #pragma unroll
;                     for (int n = 0; n < 2; ++n) acc[a][b][m][n] = (f32x4){0.f, 0.f, 0.f, 0.f};
;         cur = nxt; cA = nA; cB = nB; ++ui;
;         if constexpr (ALIGN_EPI) { if (wr == 1) PG8_BAR; }
.LBB0_404:
	s_or_b64 exec, exec, s[30:31]
	s_and_b64 vcc, exec, s[40:41]
	s_mov_b64 s[28:29], -1
	s_cbranch_vccnz .LBB0_360
	s_mov_b32 s96, 0
	s_andn2_b64 vcc, exec, s[22:23]
	s_cbranch_vccnz .LBB0_359
	s_mov_b32 s96, 1
	s_branch .LBB0_359

; #define PG8_STAGE(bufoff, gbase, voff) do { _Pragma("unroll") for (int _i = 0; _i < 2; ++_i) \
;         __builtin_amdgcn_global_load_lds((const unsigned*)((const char*)(gbase) + (voff)[_i]), (PG8_LAS unsigned*)(lds + (bufoff) + ldsw + _i * 8192), 16, 0, 0); } while (0)
; #define PG8_WAIT_V(n) asm volatile("s_waitcnt vmcnt(" #n ")" ::: "memory")
; #define PG8_BAR __builtin_amdgcn_s_barrier()
; template <class Epi, class Sched, bool ALIGN_EPI = false, bool SP2 = false>
; __device__ __forceinline__ void gemm_phase(PG8_LAS unsigned char* lds, const Gemm g, const Sched& S, const Epi& E) {
;     ...
;     const int aoff = lds_byte(wr * 64 + fr, fq * 8), boff = lds_byte(wc * 32 + fr, fq * 8);
;     ...
;         PG8_WAIT_V(2); PG8_BAR;
;         PG8_STAGE(PG8_SB(1, 0), cB + kstep, voffB); PG8_STAGE(PG8_SA(1, 0), cA + kstep, voffA); PG8_STAGE(PG8_SB(1, 1), cB + hstep + kstep, voffB);
;         PG8_WAIT_V(6); PG8_BAR;
.LBB0_500:
	s_add_i32 m0, s39, 0x18000
	v_lshl_add_u64 v[0:1], v[0:1], 0, s[20:21]
	s_waitcnt vmcnt(2)
	s_barrier
	global_load_lds_dwordx4 v[0:1], off
	v_lshl_add_u64 v[0:1], v[2:3], 0, s[20:21]
	s_add_i32 m0, s39, 0x1a000
	s_add_i32 s58, s39, 0x8000
	global_load_lds_dwordx4 v[0:1], off
	v_lshl_add_u64 v[0:1], v[8:9], 0, s[20:21]
	s_mov_b32 m0, s58
	s_add_i32 s59, s39, 0xa000
	global_load_lds_dwordx4 v[0:1], off
	v_lshl_add_u64 v[0:1], v[10:11], 0, s[20:21]
	s_mov_b32 m0, s59
	v_and_b32_e32 v2, 15, v12
	global_load_lds_dwordx4 v[0:1], off
	s_add_i32 m0, s39, 0x1c000
	v_lshl_add_u64 v[0:1], v[4:5], 0, s[20:21]
	global_load_lds_dwordx4 v[0:1], off
	v_lshl_add_u64 v[0:1], v[6:7], 0, s[20:21]
	s_add_i32 m0, s39, 0x1e000
	s_lshr_b32 s1, s1, 26
	global_load_lds_dwordx4 v[0:1], off
	v_bfe_u32 v1, v12, 4, 2
	v_lshlrev_b32_e32 v208, 4, v1
	s_add_i32 s1, s0, s1
	v_lshl_or_b32 v149, s40, 6, v2
	v_lshlrev_b32_e32 v0, 3, v1
	v_lshl_or_b32 v1, v2, 6, v208
	v_lshlrev_b32_e32 v2, 2, v12
	s_ashr_i32 s60, s1, 6
	s_lshl_b32 s1, s40, 13
	v_and_b32_e32 v2, 32, v2
	v_bitop3_b32 v3, v1, s1, v2 bitop3:0xde
	s_lshl_b32 s1, s27, 5
	s_and_b32 s1, s1, 0x60
	s_lshl_b32 s27, s1, 7
	v_readlane_b32 s40, v252, 38
	v_bitop3_b32 v153, v1, s27, v2 bitop3:0xde
	s_cmp_gt_i32 s0, 63
	v_readlane_b32 s41, v252, 39
	v_add_u32_e32 v1, v18, v16
	s_waitcnt vmcnt(6)
	s_cselect_b64 s[50:51], -1, 0
	s_add_i32 s61, s60, -2
	v_lshl_add_u64 v[136:137], s[40:41], 0, v[208:209]
	v_add_lshl_u32 v208, v1, v17, 1
	v_add_u32_e32 v1, v15, v13
	s_cmpk_lt_u32 s18, 0x100
	v_lshl_add_u64 v[138:139], s[28:29], 0, v[208:209]
	v_add_lshl_u32 v208, v1, v14, 1
	s_cselect_b64 s[52:53], -1, 0
	s_ashr_i32 s27, s26, 31
	v_lshl_add_u64 v[140:141], s[28:29], 0, v[208:209]
	s_mov_b32 s62, 0
	v_add_u32_e32 v157, 0, v3
	s_lshl_b32 s18, s1, 1
	v_lshlrev_b32_e32 v208, 1, v0
	s_barrier
	s_mov_b32 s73, 0
	s_branch .LBB0_503

; #define PG8_BAR __builtin_amdgcn_s_barrier()
; template <class Epi, class Sched, bool ALIGN_EPI = false, bool SP2 = false>
; __device__ __forceinline__ void gemm_phase(PG8_LAS unsigned char* lds, const Gemm g, const Sched& S, const Epi& E) {
;     ...
;                     for (int n = 0; n < 2; ++n) acc[a][b][m][n] = (f32x4){0.f, 0.f, 0.f, 0.f};
;         cur = nxt; cA = nA; cB = nB; ++ui;
;         if constexpr (ALIGN_EPI) { if (wr == 1) PG8_BAR; }
.LBB0_509:
	s_cmp_eq_u32 s73, 1
	s_cbranch_scc0 .Lno_restore_bar_2
	s_barrier

; __device__ __forceinline__ u32x2 pack4(const f32x4 v) { u32x2 w; w.x = cvt_pk_bf16(v[0], v[1]); w.y = cvt_pk_bf16(v[2], v[3]); return w; }
; template <int NP> __device__ __forceinline__ void load_rstd8(const float* ss, const Unit& u, int wr, int fr, int fq, float inv_n, float (&rs)[2][4]) {
;     f32x4 v[2][4];
; #pragma unroll
;     for (int ai = 0; ai < 2; ++ai)
; #pragma unroll
;         for (int m = 0; m < 4; ++m) { const int row = u.pm * BM + ai * HALF + wr * 64 + m * 16 + fr; v[ai][m] = *(const f32x4*)(ss + (size_t)row * NP + (NP == 16 ? 4 * fq : 0)); }
; #pragma unroll
;     for (int ai = 0; ai < 2; ++ai)
; #pragma unroll
;         for (int m = 0; m < 4; ++m) { float t = (v[ai][m][0] + v[ai][m][1]) + (v[ai][m][2] + v[ai][m][3]); if (NP == 16) t = quad_sum(t); rs[ai][m] = __builtin_amdgcn_rsqf(t * inv_n + kEps); }
; }
;     __device__ __forceinline__ void operator()(const f32x4 (&acc)[2][2][4][2], const Unit& u, int wr, int wc, int fr, int fq) const {
;         float rsv[2][4]; load_rstd8<16>(ss, u, wr, fr, fq, 1.0f / 1024.0f, rsv);
;         typedef unsigned u32x4_ __attribute__((ext_vector_type(4)));
; #pragma unroll
;         for (int ai = 0; ai < 2; ++ai)
; #pragma unroll
;             for (int m = 0; m < 4; ++m) {
;                 const int row = u.pm * BM + ai * HALF + wr * 64 + m * 16 + fr;
;                 const float rs = rsv[ai][m];
; #pragma unroll
;                 for (int bj = 0; bj < 2; ++bj) {
;                     const u32x2 lo = pack4(acc[ai][bj][m][0] * rs), hi = pack4(acc[ai][bj][m][1] * rs);
;                     *(u32x4_*)(O + (size_t)row * ldc + u.pn * BM + bj * HALF + wc * 32 + fq * 8) = (u32x4_){lo.x, lo.y, hi.x, hi.y};
;                 }
;             }
;     }
.LBB0_514:
	v_lshl_add_u32 v198, s66, 8, v149
	v_ashrrev_i32_e32 v199, 31, v198
	v_or_b32_e32 v164, 16, v198
	v_lshlrev_b64 v[142:143], 6, v[198:199]
	v_ashrrev_i32_e32 v165, 31, v164
	v_or_b32_e32 v160, 32, v198
	v_lshl_add_u64 v[142:143], v[136:137], 0, v[142:143]
	v_lshlrev_b64 v[144:145], 6, v[164:165]
	v_ashrrev_i32_e32 v161, 31, v160
	v_or_b32_e32 v154, 48, v198
	v_lshl_add_u64 v[144:145], v[136:137], 0, v[144:145]
	global_load_dwordx4 v[166:169], v[142:143], off
	global_load_dwordx4 v[170:173], v[144:145], off
	v_lshlrev_b64 v[142:143], 6, v[160:161]
	v_ashrrev_i32_e32 v155, 31, v154
	v_add_u32_e32 v150, 0x80, v198
	v_lshl_add_u64 v[142:143], v[136:137], 0, v[142:143]
	v_lshlrev_b64 v[144:145], 6, v[154:155]
	v_ashrrev_i32_e32 v151, 31, v150
	v_lshl_add_u64 v[144:145], v[136:137], 0, v[144:145]
	global_load_dwordx4 v[174:177], v[142:143], off
	global_load_dwordx4 v[178:181], v[144:145], off
	v_lshlrev_b64 v[142:143], 6, v[150:151]
	v_lshl_add_u64 v[142:143], v[136:137], 0, v[142:143]
	global_load_dwordx4 v[182:185], v[142:143], off
	v_add_u32_e32 v146, 0x90, v198
	v_ashrrev_i32_e32 v147, 31, v146
	v_lshlrev_b64 v[142:143], 6, v[146:147]
	v_lshl_add_u64 v[142:143], v[136:137], 0, v[142:143]
	global_load_dwordx4 v[186:189], v[142:143], off
	v_add_u32_e32 v144, 0xa0, v198
	v_add_u32_e32 v142, 0xb0, v198
	v_ashrrev_i32_e32 v145, 31, v144
	v_ashrrev_i32_e32 v143, 31, v142
	v_lshlrev_b64 v[158:159], 6, v[144:145]
	v_lshlrev_b64 v[162:163], 6, v[142:143]
	v_lshl_add_u64 v[158:159], v[136:137], 0, v[158:159]
	v_lshl_add_u64 v[162:163], v[136:137], 0, v[162:163]
	global_load_dwordx4 v[190:193], v[158:159], off
	global_load_dwordx4 v[194:197], v[162:163], off
	s_lshl_b32 s30, s65, 8
	s_ashr_i32 s31, s30, 31
	s_lshl_b64 s[30:31], s[30:31], 1
	s_and_b64 vcc, exec, s[40:41]
	s_waitcnt vmcnt(0)
	v_add_f32_e32 v143, v166, v167
	v_add_f32_e32 v145, v168, v169
	v_add_f32_e32 v143, v143, v145
	v_add_f32_e32 v145, v170, v171
	v_add_f32_e32 v147, v172, v173
	v_mov_b32_e32 v159, v143
	v_add_f32_e32 v145, v145, v147
	s_nop 0
	v_permlane16_swap_b32_e32 v143, v159
	v_add_f32_e32 v148, v174, v175
	v_add_f32_e32 v151, v176, v177
	v_add_f32_e32 v152, v178, v179
	v_add_f32_e32 v155, v180, v181
	v_add_f32_e32 v147, v148, v151
	v_add_f32_e32 v148, v152, v155
	v_mov_b32_e32 v152, v145
	v_add_f32_e32 v156, v182, v183
	v_add_f32_e32 v158, v184, v185
	v_add_f32_e32 v143, v143, v159
	v_permlane16_swap_b32_e32 v145, v152
	v_add_f32_e32 v151, v156, v158
	v_mov_b32_e32 v158, v143
	v_add_f32_e32 v145, v145, v152
	v_mov_b32_e32 v155, v147
	v_permlane32_swap_b32_e32 v143, v158
	v_mov_b32_e32 v152, v145
	v_permlane16_swap_b32_e32 v147, v155
	v_add_f32_e32 v143, v143, v158
	v_permlane32_swap_b32_e32 v145, v152
	v_add_f32_e32 v147, v147, v155
	v_fmamk_f32 v143, v143, 0x3a800000, v240
	v_add_f32_e32 v145, v145, v152
	v_mov_b32_e32 v155, v147
	v_rsq_f32_e32 v166, v143
	v_fmamk_f32 v143, v145, 0x3a800000, v240
	v_permlane32_swap_b32_e32 v147, v155
	v_rsq_f32_e32 v168, v143
	v_mov_b32_e32 v143, v151
	v_add_f32_e32 v147, v147, v155
	s_nop 0
	v_permlane16_swap_b32_e32 v151, v143
	v_fmamk_f32 v145, v147, 0x3a800000, v240
	v_add_f32_e32 v143, v151, v143
	v_rsq_f32_e32 v170, v145
	v_mov_b32_e32 v145, v143
	s_nop 1
	v_permlane32_swap_b32_e32 v143, v145
	v_add_f32_e32 v143, v143, v145
	v_fmamk_f32 v143, v143, 0x3a800000, v240
	v_rsq_f32_e32 v158, v143
	v_add_f32_e32 v143, v186, v187
	v_add_f32_e32 v145, v188, v189
	v_add_f32_e32 v143, v143, v145
	v_mov_b32_e32 v145, v143
	v_pk_mul_f32 v[126:127], v[126:127], v[166:167] op_sel_hi:[1,0]
	v_pk_mul_f32 v[124:125], v[124:125], v[166:167] op_sel_hi:[1,0]
	v_pk_mul_f32 v[120:121], v[120:121], v[166:167] op_sel_hi:[1,0]
	v_permlane16_swap_b32_e32 v143, v145
	v_cvt_pk_bf16_f32 v124, v124, v125
	v_cvt_pk_bf16_f32 v125, v126, v127
	v_pk_mul_f32 v[122:123], v[122:123], v[166:167] op_sel_hi:[1,0]
	v_cvt_pk_bf16_f32 v126, v120, v121
	v_mov_b64_e32 v[120:121], s[90:91]
	v_mov_b32_e32 v156, v148
	v_add_f32_e32 v143, v143, v145
	v_cvt_pk_bf16_f32 v127, v122, v123
	v_mad_i64_i32 v[122:123], s[34:35], v198, s78, v[120:121]
	v_permlane16_swap_b32_e32 v148, v156
	v_mov_b32_e32 v145, v143
	v_lshl_add_u64 v[122:123], v[122:123], 0, s[30:31]
	v_add_f32_e32 v148, v148, v156
	v_permlane32_swap_b32_e32 v143, v145
	v_lshl_add_u64 v[122:123], v[122:123], 0, s[18:19]
	v_mov_b32_e32 v156, v148
	v_add_f32_e32 v143, v143, v145
	v_lshl_add_u64 v[122:123], v[122:123], 0, v[208:209]
	v_pk_mul_f32 v[118:119], v[118:119], v[166:167] op_sel_hi:[1,0]
	v_pk_mul_f32 v[116:117], v[116:117], v[166:167] op_sel_hi:[1,0]
	v_pk_mul_f32 v[110:111], v[110:111], v[168:169] op_sel_hi:[1,0]
	v_pk_mul_f32 v[108:109], v[108:109], v[168:169] op_sel_hi:[1,0]
	v_pk_mul_f32 v[104:105], v[104:105], v[168:169] op_sel_hi:[1,0]
	v_permlane32_swap_b32_e32 v148, v156
	v_fmamk_f32 v143, v143, 0x3a800000, v240
	global_store_dwordx4 v[122:123], v[124:127], off
	v_cvt_pk_bf16_f32 v116, v116, v117
	v_cvt_pk_bf16_f32 v117, v118, v119
	v_pk_mul_f32 v[114:115], v[114:115], v[166:167] op_sel_hi:[1,0]
	v_pk_mul_f32 v[112:113], v[112:113], v[166:167] op_sel_hi:[1,0]
	v_add_f32_e32 v148, v148, v156
	v_cvt_pk_bf16_f32 v118, v112, v113
	v_cvt_pk_bf16_f32 v119, v114, v115
	global_store_dwordx4 v[122:123], v[116:119], off offset:256
	v_cvt_pk_bf16_f32 v108, v108, v109
	v_cvt_pk_bf16_f32 v109, v110, v111
	v_cvt_pk_bf16_f32 v110, v104, v105
	v_mad_i64_i32 v[104:105], s[34:35], v164, s78, v[120:121]
	v_rsq_f32_e32 v156, v143
	v_add_f32_e32 v143, v190, v191
	v_add_f32_e32 v145, v192, v193
	v_lshl_add_u64 v[104:105], v[104:105], 0, s[30:31]
	v_fmamk_f32 v147, v148, 0x3a800000, v240
	v_add_f32_e32 v143, v143, v145
; __device__ __forceinline__ u32x2 pack4(const f32x4 v) { u32x2 w; w.x = cvt_pk_bf16(v[0], v[1]); w.y = cvt_pk_bf16(v[2], v[3]); return w; }
;     __device__ __forceinline__ void operator()(const f32x4 (&acc)[2][2][4][2], const Unit& u, int wr, int wc, int fr, int fq) const {
;     ...
;         for (int ai = 0; ai < 2; ++ai)
; #pragma unroll
;             for (int m = 0; m < 4; ++m) {
;                 const int row = u.pm * BM + ai * HALF + wr * 64 + m * 16 + fr;
;                 const float rs = rsv[ai][m];
; #pragma unroll
;                 for (int bj = 0; bj < 2; ++bj) {
;                     const u32x2 lo = pack4(acc[ai][bj][m][0] * rs), hi = pack4(acc[ai][bj][m][1] * rs);
;                     *(u32x4_*)(O + (size_t)row * ldc + u.pn * BM + bj * HALF + wc * 32 + fq * 8) = (u32x4_){lo.x, lo.y, hi.x, hi.y};
;                 }
	v_lshl_add_u64 v[104:105], v[104:105], 0, s[18:19]
	v_rsq_f32_e32 v162, v147
	v_mov_b32_e32 v145, v143
	v_lshl_add_u64 v[104:105], v[104:105], 0, v[208:209]
	v_pk_mul_f32 v[102:103], v[102:103], v[168:169] op_sel_hi:[1,0]
	v_pk_mul_f32 v[100:101], v[100:101], v[168:169] op_sel_hi:[1,0]
	v_pk_mul_f32 v[94:95], v[94:95], v[170:171] op_sel_hi:[1,0]
	v_pk_mul_f32 v[92:93], v[92:93], v[170:171] op_sel_hi:[1,0]
	v_pk_mul_f32 v[88:89], v[88:89], v[170:171] op_sel_hi:[1,0]
	v_permlane16_swap_b32_e32 v143, v145
	v_pk_mul_f32 v[106:107], v[106:107], v[168:169] op_sel_hi:[1,0]
	v_pk_mul_f32 v[98:99], v[98:99], v[168:169] op_sel_hi:[1,0]
	v_cvt_pk_bf16_f32 v111, v106, v107
	global_store_dwordx4 v[104:105], v[108:111], off
	v_cvt_pk_bf16_f32 v100, v100, v101
	v_cvt_pk_bf16_f32 v101, v102, v103
	v_pk_mul_f32 v[96:97], v[96:97], v[168:169] op_sel_hi:[1,0]
	v_add_f32_e32 v143, v143, v145
	v_cvt_pk_bf16_f32 v102, v96, v97
	v_cvt_pk_bf16_f32 v103, v98, v99
	global_store_dwordx4 v[104:105], v[100:103], off offset:256
	v_cvt_pk_bf16_f32 v92, v92, v93
	v_cvt_pk_bf16_f32 v93, v94, v95
	v_cvt_pk_bf16_f32 v94, v88, v89
	v_mad_i64_i32 v[88:89], s[34:35], v160, s78, v[120:121]
	v_lshl_add_u64 v[88:89], v[88:89], 0, s[30:31]
	v_mov_b32_e32 v145, v143
	v_lshl_add_u64 v[88:89], v[88:89], 0, s[18:19]
	s_nop 0
	v_permlane32_swap_b32_e32 v143, v145
	v_lshl_add_u64 v[88:89], v[88:89], 0, v[208:209]
	v_pk_mul_f32 v[86:87], v[86:87], v[170:171] op_sel_hi:[1,0]
	v_pk_mul_f32 v[84:85], v[84:85], v[170:171] op_sel_hi:[1,0]
	v_pk_mul_f32 v[78:79], v[78:79], v[162:163] op_sel_hi:[1,0]
	v_pk_mul_f32 v[76:77], v[76:77], v[162:163] op_sel_hi:[1,0]
	v_pk_mul_f32 v[72:73], v[72:73], v[162:163] op_sel_hi:[1,0]
	v_add_f32_e32 v143, v143, v145
	v_pk_mul_f32 v[90:91], v[90:91], v[170:171] op_sel_hi:[1,0]
	v_pk_mul_f32 v[82:83], v[82:83], v[170:171] op_sel_hi:[1,0]
	v_cvt_pk_bf16_f32 v95, v90, v91
	global_store_dwordx4 v[88:89], v[92:95], off
	v_cvt_pk_bf16_f32 v84, v84, v85
	v_cvt_pk_bf16_f32 v85, v86, v87
	v_pk_mul_f32 v[80:81], v[80:81], v[170:171] op_sel_hi:[1,0]
	v_fmamk_f32 v143, v143, 0x3a800000, v240
	v_cvt_pk_bf16_f32 v86, v80, v81
	v_cvt_pk_bf16_f32 v87, v82, v83
	global_store_dwordx4 v[88:89], v[84:87], off offset:256
	v_cvt_pk_bf16_f32 v76, v76, v77
	v_cvt_pk_bf16_f32 v77, v78, v79
	v_cvt_pk_bf16_f32 v78, v72, v73
	v_mad_i64_i32 v[72:73], s[34:35], v154, s78, v[120:121]
	v_lshl_add_u64 v[72:73], v[72:73], 0, s[30:31]
	v_rsq_f32_e32 v152, v143
	v_add_f32_e32 v143, v194, v195
	v_add_f32_e32 v145, v196, v197
	v_lshl_add_u64 v[72:73], v[72:73], 0, s[18:19]
	v_add_f32_e32 v143, v143, v145
	v_lshl_add_u64 v[72:73], v[72:73], 0, v[208:209]
	v_pk_mul_f32 v[70:71], v[70:71], v[162:163] op_sel_hi:[1,0]
	v_pk_mul_f32 v[68:69], v[68:69], v[162:163] op_sel_hi:[1,0]
	v_pk_mul_f32 v[62:63], v[62:63], v[158:159] op_sel_hi:[1,0]
	v_pk_mul_f32 v[60:61], v[60:61], v[158:159] op_sel_hi:[1,0]
	v_pk_mul_f32 v[56:57], v[56:57], v[158:159] op_sel_hi:[1,0]
	v_mov_b32_e32 v145, v143
	v_pk_mul_f32 v[74:75], v[74:75], v[162:163] op_sel_hi:[1,0]
	v_pk_mul_f32 v[66:67], v[66:67], v[162:163] op_sel_hi:[1,0]
	v_cvt_pk_bf16_f32 v79, v74, v75
	global_store_dwordx4 v[72:73], v[76:79], off
	v_cvt_pk_bf16_f32 v68, v68, v69
	v_cvt_pk_bf16_f32 v69, v70, v71
	v_pk_mul_f32 v[64:65], v[64:65], v[162:163] op_sel_hi:[1,0]
	v_permlane16_swap_b32_e32 v143, v145
	v_cvt_pk_bf16_f32 v70, v64, v65
	v_cvt_pk_bf16_f32 v71, v66, v67
	global_store_dwordx4 v[72:73], v[68:71], off offset:256
	v_cvt_pk_bf16_f32 v60, v60, v61
	v_cvt_pk_bf16_f32 v61, v62, v63
	v_cvt_pk_bf16_f32 v62, v56, v57
	v_mad_i64_i32 v[56:57], s[34:35], v150, s78, v[120:121]
	v_lshl_add_u64 v[56:57], v[56:57], 0, s[30:31]
	v_add_f32_e32 v143, v143, v145
	v_lshl_add_u64 v[56:57], v[56:57], 0, s[18:19]
	v_mov_b32_e32 v145, v143
	v_lshl_add_u64 v[56:57], v[56:57], 0, v[208:209]
	v_pk_mul_f32 v[54:55], v[54:55], v[158:159] op_sel_hi:[1,0]
; __device__ __forceinline__ u32x2 pack4(const f32x4 v) { u32x2 w; w.x = cvt_pk_bf16(v[0], v[1]); w.y = cvt_pk_bf16(v[2], v[3]); return w; }
; #define PG8_BAR __builtin_amdgcn_s_barrier()
;     __device__ __forceinline__ void operator()(const f32x4 (&acc)[2][2][4][2], const Unit& u, int wr, int wc, int fr, int fq) const {
;     ...
;         for (int ai = 0; ai < 2; ++ai)
; #pragma unroll
;             for (int m = 0; m < 4; ++m) {
;                 const int row = u.pm * BM + ai * HALF + wr * 64 + m * 16 + fr;
;                 const float rs = rsv[ai][m];
; #pragma unroll
;                 for (int bj = 0; bj < 2; ++bj) {
;                     const u32x2 lo = pack4(acc[ai][bj][m][0] * rs), hi = pack4(acc[ai][bj][m][1] * rs);
;                     *(u32x4_*)(O + (size_t)row * ldc + u.pn * BM + bj * HALF + wc * 32 + fq * 8) = (u32x4_){lo.x, lo.y, hi.x, hi.y};
;                 }
; template <class Epi, class Sched, bool ALIGN_EPI = false, bool SP2 = false>
; __device__ __forceinline__ void gemm_phase(PG8_LAS unsigned char* lds, const Gemm g, const Sched& S, const Epi& E) {
;     ...
;         if constexpr (!Epi::AFTER_DRAIN) { E(acc, cur, wr, wc, fr, fq); S.done(cur); }
;         if (!has_next) break;
; #pragma unroll
;         for (int a = 0; a < 2; ++a)
; #pragma unroll
;             for (int b = 0; b < 2; ++b)
; #pragma unroll
;                 for (int m = 0; m < 4; ++m)
; #pragma unroll
;                     for (int n = 0; n < 2; ++n) acc[a][b][m][n] = (f32x4){0.f, 0.f, 0.f, 0.f};
;         cur = nxt; cA = nA; cB = nB; ++ui;
;         if constexpr (ALIGN_EPI) { if (wr == 1) PG8_BAR; }
	v_pk_mul_f32 v[52:53], v[52:53], v[158:159] op_sel_hi:[1,0]
	v_pk_mul_f32 v[46:47], v[46:47], v[156:157] op_sel_hi:[1,0]
	v_pk_mul_f32 v[44:45], v[44:45], v[156:157] op_sel_hi:[1,0]
	v_pk_mul_f32 v[40:41], v[40:41], v[156:157] op_sel_hi:[1,0]
	v_permlane32_swap_b32_e32 v143, v145
	v_pk_mul_f32 v[58:59], v[58:59], v[158:159] op_sel_hi:[1,0]
	v_pk_mul_f32 v[50:51], v[50:51], v[158:159] op_sel_hi:[1,0]
	v_cvt_pk_bf16_f32 v63, v58, v59
	global_store_dwordx4 v[56:57], v[60:63], off
	v_cvt_pk_bf16_f32 v52, v52, v53
	v_cvt_pk_bf16_f32 v53, v54, v55
	v_pk_mul_f32 v[48:49], v[48:49], v[158:159] op_sel_hi:[1,0]
	v_add_f32_e32 v143, v143, v145
	v_cvt_pk_bf16_f32 v54, v48, v49
	v_cvt_pk_bf16_f32 v55, v50, v51
	global_store_dwordx4 v[56:57], v[52:55], off offset:256
	v_cvt_pk_bf16_f32 v44, v44, v45
	v_cvt_pk_bf16_f32 v45, v46, v47
	v_cvt_pk_bf16_f32 v46, v40, v41
	v_mad_i64_i32 v[40:41], s[34:35], v146, s78, v[120:121]
	v_lshl_add_u64 v[40:41], v[40:41], 0, s[30:31]
	v_fmamk_f32 v143, v143, 0x3a800000, v240
	v_lshl_add_u64 v[40:41], v[40:41], 0, s[18:19]
	v_rsq_f32_e32 v148, v143
	v_lshl_add_u64 v[40:41], v[40:41], 0, v[208:209]
	v_pk_mul_f32 v[38:39], v[38:39], v[156:157] op_sel_hi:[1,0]
	v_pk_mul_f32 v[36:37], v[36:37], v[156:157] op_sel_hi:[1,0]
	v_pk_mul_f32 v[30:31], v[30:31], v[152:153] op_sel_hi:[1,0]
	v_pk_mul_f32 v[28:29], v[28:29], v[152:153] op_sel_hi:[1,0]
	v_pk_mul_f32 v[24:25], v[24:25], v[152:153] op_sel_hi:[1,0]
	v_pk_mul_f32 v[42:43], v[42:43], v[156:157] op_sel_hi:[1,0]
	v_pk_mul_f32 v[34:35], v[34:35], v[156:157] op_sel_hi:[1,0]
	v_cvt_pk_bf16_f32 v47, v42, v43
	global_store_dwordx4 v[40:41], v[44:47], off
	v_cvt_pk_bf16_f32 v36, v36, v37
	v_cvt_pk_bf16_f32 v37, v38, v39
	v_pk_mul_f32 v[32:33], v[32:33], v[156:157] op_sel_hi:[1,0]
	v_pk_mul_f32 v[22:23], v[22:23], v[152:153] op_sel_hi:[1,0]
	v_cvt_pk_bf16_f32 v38, v32, v33
	v_cvt_pk_bf16_f32 v39, v34, v35
	global_store_dwordx4 v[40:41], v[36:39], off offset:256
	v_cvt_pk_bf16_f32 v28, v28, v29
	v_cvt_pk_bf16_f32 v29, v30, v31
	v_cvt_pk_bf16_f32 v30, v24, v25
	v_mad_i64_i32 v[24:25], s[34:35], v144, s78, v[120:121]
	v_lshl_add_u64 v[24:25], v[24:25], 0, s[30:31]
	v_lshl_add_u64 v[24:25], v[24:25], 0, s[18:19]
	v_lshl_add_u64 v[24:25], v[24:25], 0, v[208:209]
	v_pk_mul_f32 v[20:21], v[20:21], v[152:153] op_sel_hi:[1,0]
	v_pk_mul_f32 v[14:15], v[14:15], v[148:149] op_sel_hi:[1,0]
	v_pk_mul_f32 v[12:13], v[12:13], v[148:149] op_sel_hi:[1,0]
	v_pk_mul_f32 v[8:9], v[8:9], v[148:149] op_sel_hi:[1,0]
	v_pk_mul_f32 v[26:27], v[26:27], v[152:153] op_sel_hi:[1,0]
	v_pk_mul_f32 v[18:19], v[18:19], v[152:153] op_sel_hi:[1,0]
	v_cvt_pk_bf16_f32 v31, v26, v27
	global_store_dwordx4 v[24:25], v[28:31], off
	v_cvt_pk_bf16_f32 v20, v20, v21
	v_cvt_pk_bf16_f32 v21, v22, v23
	v_pk_mul_f32 v[16:17], v[16:17], v[152:153] op_sel_hi:[1,0]
	v_pk_mul_f32 v[6:7], v[6:7], v[148:149] op_sel_hi:[1,0]
	v_cvt_pk_bf16_f32 v22, v16, v17
	v_cvt_pk_bf16_f32 v23, v18, v19
	global_store_dwordx4 v[24:25], v[20:23], off offset:256
	v_cvt_pk_bf16_f32 v12, v12, v13
	v_cvt_pk_bf16_f32 v13, v14, v15
	v_cvt_pk_bf16_f32 v14, v8, v9
	v_mad_i64_i32 v[8:9], s[34:35], v142, s78, v[120:121]
	v_lshl_add_u64 v[8:9], v[8:9], 0, s[30:31]
	v_lshl_add_u64 v[8:9], v[8:9], 0, s[18:19]
	v_lshl_add_u64 v[8:9], v[8:9], 0, v[208:209]
	v_pk_mul_f32 v[4:5], v[4:5], v[148:149] op_sel_hi:[1,0]
	s_mov_b64 s[30:31], -1
	v_pk_mul_f32 v[10:11], v[10:11], v[148:149] op_sel_hi:[1,0]
	v_pk_mul_f32 v[2:3], v[2:3], v[148:149] op_sel_hi:[1,0]
	v_cvt_pk_bf16_f32 v15, v10, v11
	global_store_dwordx4 v[8:9], v[12:15], off
	v_cvt_pk_bf16_f32 v4, v4, v5
	v_cvt_pk_bf16_f32 v5, v6, v7
	v_pk_mul_f32 v[0:1], v[0:1], v[148:149] op_sel_hi:[1,0]
	s_nop 0
	v_cvt_pk_bf16_f32 v6, v0, v1
	v_cvt_pk_bf16_f32 v7, v2, v3
	global_store_dwordx4 v[8:9], v[4:7], off offset:256
	s_cbranch_vccnz .LBB0_502
	s_mov_b32 s73, 0
	s_andn2_b64 vcc, exec, s[44:45]
	s_cbranch_vccnz .LBB0_501
	s_mov_b32 s73, 1
	s_branch .LBB0_501

; #define PG8_STAGE(bufoff, gbase, voff) do { _Pragma("unroll") for (int _i = 0; _i < 2; ++_i) \
;         __builtin_amdgcn_global_load_lds((const unsigned*)((const char*)(gbase) + (voff)[_i]), (PG8_LAS unsigned*)(lds + (bufoff) + ldsw + _i * 8192), 16, 0, 0); } while (0)
; #define PG8_WAIT_V(n) asm volatile("s_waitcnt vmcnt(" #n ")" ::: "memory")
; #define PG8_BAR __builtin_amdgcn_s_barrier()
;     __device__ __forceinline__ void operator()(const f32x4 (&acc)[2][2][4][2], const Unit& u, int wr, int wc, int fr, int fq) const {
;         float* wl = wlds + (wr * 4 + wc) * 576;
;         const int lane = fq * 16 + fr, rl = lane >> 3, ch = lane & 7;
;         f32x4 rb[2][2][2][2];
;         const size_t cbase = (size_t)u.pn * BM + wc * 32 + ch * 4;
; template <class Epi, class Sched, bool ALIGN_EPI = false, bool SP2 = false>
; __device__ __forceinline__ void gemm_phase(PG8_LAS unsigned char* lds, const Gemm g, const Sched& S, const Epi& E) {
;     ...
;         PG8_WAIT_V(2); PG8_BAR;
;         PG8_STAGE(PG8_SB(1, 0), cB + kstep, voffB); PG8_STAGE(PG8_SA(1, 0), cA + kstep, voffA); PG8_STAGE(PG8_SB(1, 1), cB + hstep + kstep, voffB);
;         PG8_WAIT_V(6); PG8_BAR;
.LBB0_746:
	s_cmp_eq_u32 s3, 2
	s_cselect_b64 s[42:43], -1, 0
	s_add_i32 m0, s8, 0x18000
	v_lshl_add_u64 v[0:1], v[0:1], 0, s[20:21]
	s_waitcnt vmcnt(2)
	s_barrier
	global_load_lds_dwordx4 v[0:1], off
	v_lshl_add_u64 v[0:1], v[2:3], 0, s[20:21]
	s_add_i32 m0, s8, 0x1a000
	s_add_i32 s37, s8, 0x8000
	global_load_lds_dwordx4 v[0:1], off
	v_lshl_add_u64 v[0:1], v[8:9], 0, s[20:21]
	s_mov_b32 m0, s37
	s_add_i32 s38, s8, 0xa000
	global_load_lds_dwordx4 v[0:1], off
	v_lshl_add_u64 v[0:1], v[10:11], 0, s[20:21]
	s_mov_b32 m0, s38
	s_lshr_b32 s1, s1, 26
	global_load_lds_dwordx4 v[0:1], off
	s_add_i32 m0, s8, 0x1c000
	v_lshl_add_u64 v[0:1], v[4:5], 0, s[20:21]
	global_load_lds_dwordx4 v[0:1], off
	v_lshl_add_u64 v[0:1], v[6:7], 0, s[20:21]
	s_add_i32 m0, s8, 0x1e000
	s_add_i32 s1, s0, s1
	global_load_lds_dwordx4 v[0:1], off
	v_and_b32_e32 v0, 15, v12
	v_and_b32_e32 v1, 48, v12
	v_lshlrev_b32_e32 v3, 2, v12
	v_cndmask_b32_e64 v130, 1.0, 0, s[42:43]
	s_and_b32 s42, s39, 3
	s_ashr_i32 s39, s1, 6
	v_lshl_or_b32 v2, v0, 6, v1
	s_lshl_b32 s1, s41, 13
	v_and_b32_e32 v3, 32, v3
	v_bitop3_b32 v4, v2, s1, v3 bitop3:0xde
	s_lshl_b32 s1, s42, 12
	s_cmp_gt_i32 s0, 63
	s_cselect_b64 s[56:57], -1, 0
	s_add_i32 s48, s39, -2
	v_bitop3_b32 v133, v2, s1, v3 bitop3:0xde
	s_cmpk_lt_u32 s40, 0x100
	v_and_b32_e32 v3, 7, v12
	s_cselect_b64 s[58:59], -1, 0
	s_lshl_b32 s0, s41, 2
	v_lshlrev_b32_e32 v5, 2, v3
	s_or_b32 s0, s0, s42
	v_lshl_or_b32 v132, s42, 5, v5
	s_ashr_i32 s45, s44, 31
	s_lshl_b32 s1, s42, 2
	v_readlane_b32 s42, v252, 38
	v_readlane_b32 s43, v252, 39
	s_add_u32 s63, s42, s1
	s_addc_u32 s64, s43, 0
	s_lshl_b32 s66, s29, 3
	s_abs_i32 s67, s66
	v_cvt_f32_u32_e32 v5, s67
	s_mulk_i32 s0, 0x900
	v_mul_u32_u24_e32 v0, 36, v0
	s_add_i32 s0, s0, 0
	s_add_i32 s0, s0, 0x20000
	v_lshlrev_b32_e32 v0, 2, v0
	v_add3_u32 v197, s0, v0, v1
	v_rcp_iflag_f32_e32 v1, v5
	v_bfe_u32 v2, v12, 3, 3
	v_lshl_or_b32 v196, s41, 6, v2
	v_mul_u32_u24_e32 v2, 36, v2
	v_mul_f32_e32 v1, 0x4f7ffffe, v1
	v_cvt_u32_f32_e32 v1, v1
	v_lshlrev_b32_e32 v0, 4, v3
	v_lshlrev_b32_e32 v2, 2, v2
	v_add3_u32 v198, s0, v0, v2
	s_sub_i32 s0, 0, s67
	v_readfirstlane_b32 s1, v1
	s_waitcnt vmcnt(6)
	s_mul_i32 s0, s0, s1
	s_mul_hi_u32 s0, s1, s0
	s_mov_b32 s62, 0
	v_cmp_eq_u32_e64 s[40:41], 0, v3
	s_lshl_b32 s65, s29, 4
	v_mov_b32_e32 v134, v130
	v_mov_b32_e32 v135, v130
	s_bfe_i32 s68, s29, 0x1001c
	s_add_i32 s69, s1, s0
	v_lshl_add_u64 v[136:137], s[50:51], 0, v[208:209]
	v_lshl_add_u64 v[138:139], s[50:51], 0, v[128:129]
	v_add_u32_e32 v199, 0, v4
	s_barrier
	s_mov_b32 s92, 0
	s_branch .LBB0_749

; #define PG8_BAR __builtin_amdgcn_s_barrier()
; template <class Epi, class Sched, bool ALIGN_EPI = false, bool SP2 = false>
; __device__ __forceinline__ void gemm_phase(PG8_LAS unsigned char* lds, const Gemm g, const Sched& S, const Epi& E) {
;     ...
;         const bool has_next = S.next(ui + 1, nxt);
;         const char* nA = has_next ? (const char*)g.A + (size_t)nxt.pm * tstep : cA; const char* nB = has_next ? (const char*)g.Bt + (size_t)nxt.pn * tstep : cB;
;     ...
;                     for (int n = 0; n < 2; ++n) acc[a][b][m][n] = (f32x4){0.f, 0.f, 0.f, 0.f};
;         cur = nxt; cA = nA; cB = nB; ++ui;
;         if constexpr (ALIGN_EPI) { if (wr == 1) PG8_BAR; }
.LBB0_753:
	s_and_b64 vcc, exec, s[42:43]
	s_mov_b64 s[60:61], s[34:35]
	s_cbranch_vccnz .LBB0_755
	s_ashr_i32 s29, s70, 31
	s_mul_hi_u32 s60, s52, s70
	s_mul_i32 s29, s52, s29
	s_add_i32 s29, s60, s29
	s_mul_i32 s60, s53, s70
	s_add_i32 s29, s29, s60
	s_mul_i32 s60, s52, s70
	v_readlane_b32 s10, v254, 6
	s_add_u32 s60, s10, s60
	v_readlane_b32 s10, v254, 7
	s_addc_u32 s61, s10, s29
.LBB0_755:
	s_cmp_eq_u32 s92, 1
	s_cbranch_scc0 .Lno_restore_bar_3
	s_barrier
.Lno_restore_bar_3:
	s_andn2_b64 vcc, exec, s[56:57]
	s_cbranch_vccz .Lpeel_k5
	v_mov_b32_e32 v123, 0
	v_mov_b32_e32 v122, v123
	v_mov_b32_e32 v121, v123
	v_mov_b32_e32 v120, v123
	v_mov_b32_e32 v127, v123
	v_mov_b32_e32 v126, v123
	v_mov_b32_e32 v125, v123
	v_mov_b32_e32 v124, v123
	v_mov_b32_e32 v111, v123
	v_mov_b32_e32 v110, v123
	v_mov_b32_e32 v109, v123
	v_mov_b32_e32 v108, v123
	v_mov_b32_e32 v107, v123
	v_mov_b32_e32 v106, v123
	v_mov_b32_e32 v105, v123
	v_mov_b32_e32 v104, v123
	v_mov_b32_e32 v95, v123
	v_mov_b32_e32 v94, v123
	v_mov_b32_e32 v93, v123
	v_mov_b32_e32 v92, v123
	v_mov_b32_e32 v91, v123
	v_mov_b32_e32 v90, v123
	v_mov_b32_e32 v89, v123
	v_mov_b32_e32 v88, v123
	v_mov_b32_e32 v79, v123
	v_mov_b32_e32 v78, v123
	v_mov_b32_e32 v77, v123
	v_mov_b32_e32 v76, v123
	v_mov_b32_e32 v75, v123
	v_mov_b32_e32 v74, v123
	v_mov_b32_e32 v73, v123
	v_mov_b32_e32 v72, v123
	v_mov_b32_e32 v119, v123
	v_mov_b32_e32 v118, v123
	v_mov_b32_e32 v117, v123
	v_mov_b32_e32 v116, v123
	v_mov_b32_e32 v115, v123
	v_mov_b32_e32 v114, v123
	v_mov_b32_e32 v113, v123
	v_mov_b32_e32 v112, v123
	v_mov_b32_e32 v103, v123
	v_mov_b32_e32 v102, v123
	v_mov_b32_e32 v101, v123
	v_mov_b32_e32 v100, v123
	v_mov_b32_e32 v99, v123
	v_mov_b32_e32 v98, v123
	v_mov_b32_e32 v97, v123
	v_mov_b32_e32 v96, v123
	v_mov_b32_e32 v87, v123
	v_mov_b32_e32 v86, v123
	v_mov_b32_e32 v85, v123
	v_mov_b32_e32 v84, v123
	v_mov_b32_e32 v83, v123
	v_mov_b32_e32 v82, v123
	v_mov_b32_e32 v81, v123
	v_mov_b32_e32 v80, v123
	v_mov_b32_e32 v71, v123
	v_mov_b32_e32 v70, v123
	v_mov_b32_e32 v69, v123
	v_mov_b32_e32 v68, v123
	v_mov_b32_e32 v67, v123
	v_mov_b32_e32 v66, v123
	v_mov_b32_e32 v65, v123
	v_mov_b32_e32 v64, v123
	v_mov_b32_e32 v63, v123
	v_mov_b32_e32 v62, v123
	v_mov_b32_e32 v61, v123
	v_mov_b32_e32 v60, v123
	v_mov_b32_e32 v59, v123
	v_mov_b32_e32 v58, v123
	v_mov_b32_e32 v57, v123
	v_mov_b32_e32 v56, v123
	v_mov_b32_e32 v47, v123
	v_mov_b32_e32 v46, v123
	v_mov_b32_e32 v45, v123
	v_mov_b32_e32 v44, v123
	v_mov_b32_e32 v43, v123
	v_mov_b32_e32 v42, v123
	v_mov_b32_e32 v41, v123
	v_mov_b32_e32 v40, v123
	v_mov_b32_e32 v31, v123
	v_mov_b32_e32 v30, v123
	v_mov_b32_e32 v29, v123
	v_mov_b32_e32 v28, v123
	v_mov_b32_e32 v27, v123
	v_mov_b32_e32 v26, v123
	v_mov_b32_e32 v25, v123
	v_mov_b32_e32 v24, v123
	v_mov_b32_e32 v15, v123
	v_mov_b32_e32 v14, v123
	v_mov_b32_e32 v13, v123
	v_mov_b32_e32 v12, v123
	v_mov_b32_e32 v11, v123
	v_mov_b32_e32 v10, v123
	v_mov_b32_e32 v9, v123
	v_mov_b32_e32 v8, v123
	v_mov_b32_e32 v55, v123
	v_mov_b32_e32 v54, v123
	v_mov_b32_e32 v53, v123
	v_mov_b32_e32 v52, v123
	v_mov_b32_e32 v51, v123
	v_mov_b32_e32 v50, v123
	v_mov_b32_e32 v49, v123
	v_mov_b32_e32 v48, v123
	v_mov_b32_e32 v39, v123
	v_mov_b32_e32 v38, v123
	v_mov_b32_e32 v37, v123
	v_mov_b32_e32 v36, v123
	v_mov_b32_e32 v35, v123
	v_mov_b32_e32 v34, v123
	v_mov_b32_e32 v33, v123
	v_mov_b32_e32 v32, v123
	v_mov_b32_e32 v23, v123
	v_mov_b32_e32 v22, v123
	v_mov_b32_e32 v21, v123
	v_mov_b32_e32 v20, v123
	v_mov_b32_e32 v19, v123
	v_mov_b32_e32 v18, v123
	v_mov_b32_e32 v17, v123
	v_mov_b32_e32 v16, v123
	v_mov_b32_e32 v7, v123
	v_mov_b32_e32 v6, v123
	v_mov_b32_e32 v5, v123
	v_mov_b32_e32 v4, v123
	v_mov_b32_e32 v3, v123
	v_mov_b32_e32 v2, v123
	v_mov_b32_e32 v1, v123
	v_mov_b32_e32 v0, v123
	s_branch .LBB0_758

; #define PG8_BAR __builtin_amdgcn_s_barrier()
; template <class Epi, class Sched, bool ALIGN_EPI = false, bool SP2 = false>
; __device__ __forceinline__ void gemm_phase(PG8_LAS unsigned char* lds, const Gemm g, const Sched& S, const Epi& E) {
;     ...
;         if constexpr (!Epi::AFTER_DRAIN) { E(acc, cur, wr, wc, fr, fq); S.done(cur); }
;         if (!has_next) break;
; #pragma unroll
;         for (int a = 0; a < 2; ++a)
; #pragma unroll
;             for (int b = 0; b < 2; ++b)
; #pragma unroll
;                 for (int m = 0; m < 4; ++m)
; #pragma unroll
;                     for (int n = 0; n < 2; ++n) acc[a][b][m][n] = (f32x4){0.f, 0.f, 0.f, 0.f};
;         cur = nxt; cA = nA; cB = nB; ++ui;
;         if constexpr (ALIGN_EPI) { if (wr == 1) PG8_BAR; }
.LBB0_792:
	s_or_b64 exec, exec, s[30:31]
	s_and_b64 vcc, exec, s[42:43]
	s_mov_b64 s[28:29], -1
	s_cbranch_vccnz .LBB0_748
	s_mov_b32 s92, 0
	s_andn2_b64 vcc, exec, s[54:55]
	s_cbranch_vccnz .LBB0_747
	s_mov_b32 s92, 1
	s_branch .LBB0_747

; #define PG8_STAGE(bufoff, gbase, voff) do { _Pragma("unroll") for (int _i = 0; _i < 2; ++_i) \
;         __builtin_amdgcn_global_load_lds((const unsigned*)((const char*)(gbase) + (voff)[_i]), (PG8_LAS unsigned*)(lds + (bufoff) + ldsw + _i * 8192), 16, 0, 0); } while (0)
; #define PG8_WAIT_V(n) asm volatile("s_waitcnt vmcnt(" #n ")" ::: "memory")
; #define PG8_BAR __builtin_amdgcn_s_barrier()
; template <class Epi, class Sched, bool ALIGN_EPI = false, bool SP2 = false>
; __device__ __forceinline__ void gemm_phase(PG8_LAS unsigned char* lds, const Gemm g, const Sched& S, const Epi& E) {
;     ...
;     const int aoff = lds_byte(wr * 64 + fr, fq * 8), boff = lds_byte(wc * 32 + fr, fq * 8);
;     ...
;         PG8_WAIT_V(2); PG8_BAR;
;         PG8_STAGE(PG8_SB(1, 0), cB + kstep, voffB); PG8_STAGE(PG8_SA(1, 0), cA + kstep, voffA); PG8_STAGE(PG8_SB(1, 1), cB + hstep + kstep, voffB);
;         PG8_WAIT_V(6); PG8_BAR;
.LBB0_1136:
	s_add_i32 m0, s48, 0x18000
	v_lshl_add_u64 v[0:1], v[0:1], 0, s[20:21]
	s_waitcnt vmcnt(2)
	s_barrier
	global_load_lds_dwordx4 v[0:1], off
	v_lshl_add_u64 v[0:1], v[2:3], 0, s[20:21]
	s_add_i32 m0, s48, 0x1a000
	s_add_i32 s63, s48, 0x8000
	global_load_lds_dwordx4 v[0:1], off
	v_lshl_add_u64 v[0:1], v[8:9], 0, s[20:21]
	s_mov_b32 m0, s63
	s_add_i32 s64, s48, 0xa000
	global_load_lds_dwordx4 v[0:1], off
	v_lshl_add_u64 v[0:1], v[10:11], 0, s[20:21]
	s_mov_b32 m0, s64
	v_bfe_u32 v13, v12, 4, 2
	global_load_lds_dwordx4 v[0:1], off
	s_add_i32 m0, s48, 0x1c000
	v_lshl_add_u64 v[0:1], v[4:5], 0, s[20:21]
	global_load_lds_dwordx4 v[0:1], off
	v_lshl_add_u64 v[0:1], v[6:7], 0, s[20:21]
	s_add_i32 m0, s48, 0x1e000
	s_lshr_b32 s1, s1, 26
	global_load_lds_dwordx4 v[0:1], off
	v_and_b32_e32 v181, 15, v12
	s_add_i32 s1, s0, s1
	v_lshlrev_b32_e32 v14, 4, v13
	v_lshlrev_b32_e32 v12, 2, v12
	s_ashr_i32 s60, s1, 6
	v_lshl_or_b32 v14, v181, 6, v14
	s_lshl_b32 s1, s39, 13
	v_and_b32_e32 v12, 32, v12
	v_bitop3_b32 v15, v14, s1, v12 bitop3:0xde
	s_lshl_b32 s1, s38, 5
	s_and_b32 s62, s1, 0x60
	s_lshl_b32 s61, s39, 6
	s_lshl_b32 s1, s62, 7
	s_cmp_gt_i32 s0, 63
	s_waitcnt vmcnt(6)
	s_cselect_b64 s[50:51], -1, 0
	s_add_i32 s65, s60, -2
	s_cmpk_lt_u32 s27, 0x100
	v_bitop3_b32 v191, v14, s1, v12 bitop3:0xde
	s_cselect_b64 s[52:53], -1, 0
	v_lshlrev_b32_e32 v180, 2, v13
	s_ashr_i32 s27, s26, 31
	v_lshl_add_u64 v[182:183], s[42:43], 0, v[178:179]
	v_lshl_add_u64 v[184:185], s[42:43], 0, v[176:177]
	s_mov_b32 s66, 0
	v_add_u32_e32 v195, 0, v15
	s_barrier
	s_mov_b32 s82, 0
	s_branch .LBB0_1139

; #define PG8_STAGE(bufoff, gbase, voff) do { _Pragma("unroll") for (int _i = 0; _i < 2; ++_i) \
;         __builtin_amdgcn_global_load_lds((const unsigned*)((const char*)(gbase) + (voff)[_i]), (PG8_LAS unsigned*)(lds + (bufoff) + ldsw + _i * 8192), 16, 0, 0); } while (0)
; #define PG8_LDA(dst, b, h) do { _Pragma("unroll") for (int m = 0; m < 4; ++m) _Pragma("unroll") for (int k = 0; k < 2; ++k) dst[m][k] = *(const PG8_LAS bf16x8*)(lds + PG8_SA(b, h) + aoff + m * 2048 + k * 1024); } while (0)
; #define PG8_LDB(dst, b, h) do { _Pragma("unroll") for (int n = 0; n < 2; ++n) _Pragma("unroll") for (int k = 0; k < 2; ++k) dst[n][k] = *(const PG8_LAS bf16x8*)(lds + PG8_SB(b, h) + boff + n * 2048 + k * 1024); } while (0)
; #define PG8_MMA(ai, bj, At, Bt) do { __builtin_amdgcn_s_setprio(1); _Pragma("unroll") for (int m = 0; m < 4; ++m) _Pragma("unroll") for (int n = 0; n < 2; ++n) _Pragma("unroll") for (int k = 0; k < 2; ++k) \
;         acc[ai][bj][m][n] = mma16<Epi::F16>(Bt[n][k], At[m][k], acc[ai][bj][m][n]); __builtin_amdgcn_s_setprio(0); } while (0)
; #define PG8_WAIT_V(n) asm volatile("s_waitcnt vmcnt(" #n ")" ::: "memory")
; #define PG8_WAIT_L(n) asm volatile("s_waitcnt lgkmcnt(" #n ")" ::: "memory")
; #define PG8_BAR __builtin_amdgcn_s_barrier()
; #define PG8_SCHED __builtin_amdgcn_sched_barrier(0)
; template <class Epi, class Sched, bool ALIGN_EPI = false, bool SP2 = false>
; __device__ __forceinline__ void gemm_phase(PG8_LAS unsigned char* lds, const Gemm g, const Sched& S, const Epi& E) {
;     ...
;             if constexpr (SP2) {
;             PG8_LDB(B0, 0, 0); PG8_LDB(B1, 0, 1); PG8_SCHED; PG8_LDA(At, 0, 0); PG8_STAGE(PG8_SA(1, 1), a1 + hstep, voffA);
;             PG8_WAIT_V(8); PG8_WAIT_L(0); PG8_BAR; PG8_MMA(0, 0, At, B0); PG8_MMA(0, 1, At, B1); PG8_BAR; PG8_SCHED;
;     ...
;                     for (int n = 0; n < 2; ++n) acc[a][b][m][n] = (f32x4){0.f, 0.f, 0.f, 0.f};
;         cur = nxt; cA = nA; cB = nB; ++ui;
;         if constexpr (ALIGN_EPI) { if (wr == 1) PG8_BAR; }
.LBB0_1145:
	s_waitcnt vmcnt(0)
	s_cmp_eq_u32 s82, 1
	s_cbranch_scc0 .Lno_restore_bar_5
	s_barrier
.Lno_restore_bar_5:
	s_andn2_b64 vcc, exec, s[50:51]
	s_cbranch_vccz .Lpeel_k7
	v_mov_b32_e32 v127, 0
	v_mov_b32_e32 v126, v127
	v_mov_b32_e32 v125, v127
	v_mov_b32_e32 v124, v127
	v_mov_b32_e32 v123, v127
	v_mov_b32_e32 v122, v127
	v_mov_b32_e32 v121, v127
	v_mov_b32_e32 v120, v127
	v_mov_b32_e32 v111, v127
	v_mov_b32_e32 v110, v127
	v_mov_b32_e32 v109, v127
	v_mov_b32_e32 v108, v127
	v_mov_b32_e32 v107, v127
	v_mov_b32_e32 v106, v127
	v_mov_b32_e32 v105, v127
	v_mov_b32_e32 v104, v127
	v_mov_b32_e32 v95, v127
	v_mov_b32_e32 v94, v127
	v_mov_b32_e32 v93, v127
	v_mov_b32_e32 v92, v127
	v_mov_b32_e32 v91, v127
	v_mov_b32_e32 v90, v127
	v_mov_b32_e32 v89, v127
	v_mov_b32_e32 v88, v127
	v_mov_b32_e32 v79, v127
	v_mov_b32_e32 v78, v127
	v_mov_b32_e32 v77, v127
	v_mov_b32_e32 v76, v127
	v_mov_b32_e32 v75, v127
	v_mov_b32_e32 v74, v127
	v_mov_b32_e32 v73, v127
	v_mov_b32_e32 v72, v127
	v_mov_b32_e32 v119, v127
	v_mov_b32_e32 v118, v127
	v_mov_b32_e32 v117, v127
	v_mov_b32_e32 v116, v127
	v_mov_b32_e32 v115, v127
	v_mov_b32_e32 v114, v127
	v_mov_b32_e32 v113, v127
	v_mov_b32_e32 v112, v127
	v_mov_b32_e32 v103, v127
	v_mov_b32_e32 v102, v127
	v_mov_b32_e32 v101, v127
	v_mov_b32_e32 v100, v127
	v_mov_b32_e32 v99, v127
	v_mov_b32_e32 v98, v127
	v_mov_b32_e32 v97, v127
	v_mov_b32_e32 v96, v127
	v_mov_b32_e32 v87, v127
	v_mov_b32_e32 v86, v127
	v_mov_b32_e32 v85, v127
	v_mov_b32_e32 v84, v127
	v_mov_b32_e32 v83, v127
	v_mov_b32_e32 v82, v127
	v_mov_b32_e32 v81, v127
	v_mov_b32_e32 v80, v127
	v_mov_b32_e32 v71, v127
	v_mov_b32_e32 v70, v127
	v_mov_b32_e32 v69, v127
	v_mov_b32_e32 v68, v127
	v_mov_b32_e32 v67, v127
	v_mov_b32_e32 v66, v127
	v_mov_b32_e32 v65, v127
	v_mov_b32_e32 v64, v127
	v_mov_b32_e32 v63, v127
	v_mov_b32_e32 v62, v127
	v_mov_b32_e32 v61, v127
	v_mov_b32_e32 v60, v127
	v_mov_b32_e32 v59, v127
	v_mov_b32_e32 v58, v127
	v_mov_b32_e32 v57, v127
	v_mov_b32_e32 v56, v127
	v_mov_b32_e32 v47, v127
	v_mov_b32_e32 v46, v127
	v_mov_b32_e32 v45, v127
	v_mov_b32_e32 v44, v127
	v_mov_b32_e32 v43, v127
	v_mov_b32_e32 v42, v127
	v_mov_b32_e32 v41, v127
	v_mov_b32_e32 v40, v127
	v_mov_b32_e32 v31, v127
	v_mov_b32_e32 v30, v127
	v_mov_b32_e32 v29, v127
	v_mov_b32_e32 v28, v127
	v_mov_b32_e32 v27, v127
	v_mov_b32_e32 v26, v127
	v_mov_b32_e32 v25, v127
	v_mov_b32_e32 v24, v127
	v_mov_b32_e32 v15, v127
	v_mov_b32_e32 v14, v127
	v_mov_b32_e32 v13, v127
	v_mov_b32_e32 v12, v127
	v_mov_b32_e32 v11, v127
	v_mov_b32_e32 v10, v127
	v_mov_b32_e32 v9, v127
	v_mov_b32_e32 v8, v127
	v_mov_b32_e32 v55, v127
	v_mov_b32_e32 v54, v127
	v_mov_b32_e32 v53, v127
	v_mov_b32_e32 v52, v127
	v_mov_b32_e32 v51, v127
	v_mov_b32_e32 v50, v127
	v_mov_b32_e32 v49, v127
	v_mov_b32_e32 v48, v127
	v_mov_b32_e32 v39, v127
	v_mov_b32_e32 v38, v127
	v_mov_b32_e32 v37, v127
	v_mov_b32_e32 v36, v127
	v_mov_b32_e32 v35, v127
	v_mov_b32_e32 v34, v127
	v_mov_b32_e32 v33, v127
	v_mov_b32_e32 v32, v127
	v_mov_b32_e32 v23, v127
	v_mov_b32_e32 v22, v127
	v_mov_b32_e32 v21, v127
	v_mov_b32_e32 v20, v127
	v_mov_b32_e32 v19, v127
	v_mov_b32_e32 v18, v127
	v_mov_b32_e32 v17, v127
	v_mov_b32_e32 v16, v127
	v_mov_b32_e32 v7, v127
	v_mov_b32_e32 v6, v127
	v_mov_b32_e32 v5, v127
	v_mov_b32_e32 v4, v127
	v_mov_b32_e32 v3, v127
	v_mov_b32_e32 v2, v127
	v_mov_b32_e32 v1, v127
	v_mov_b32_e32 v0, v127
	s_branch .LBB0_1148
.Lpeel_k7:
	s_add_u32 s30, s30, 0x80
	s_addc_u32 s31, s31, 0
	s_add_u32 s69, s34, 0x100
	s_addc_u32 s70, s35, 0
	s_mov_b32 s34, 0
	s_add_i32 s71, s34, 2
	s_add_u32 s72, s30, 0x80
	s_addc_u32 s35, s31, 0
	s_add_i32 s77, 0, 0x10000
	s_cmp_eq_u32 s65, s34
	s_cselect_b32 s35, s1, s35
	s_cselect_b32 s34, s0, s72
	s_cselect_b32 s73, s55, s70
	s_cselect_b32 s72, s54, s69
	s_add_i32 s82, 0, 0x14000
	v_add_u32_e32 v140, s77, v191
	v_add_u32_e32 v156, s82, v191
	ds_read_b128 v[128:131], v140
	ds_read_b128 v[132:135], v140 offset:1024
	ds_read_b128 v[136:139], v140 offset:2048
	ds_read_b128 v[140:143], v140 offset:3072
	ds_read_b128 v[144:147], v156
	ds_read_b128 v[148:151], v156 offset:1024
	ds_read_b128 v[152:155], v156 offset:2048
	ds_read_b128 v[156:159], v156 offset:3072
	v_lshl_add_u64 v[192:193], s[30:31], 0, v[182:183]
	s_add_i32 m0, s48, 0xc000
	ds_read_b128 v[160:163], v195
	ds_read_b128 v[164:167], v195 offset:1024
	ds_read_b128 v[168:171], v195 offset:2048
	ds_read_b128 v[172:175], v195 offset:3072
	ds_read_b128 v[186:189], v195 offset:4096
	ds_read_b128 v[196:199], v195 offset:5120
	ds_read_b128 v[200:203], v195 offset:6144
	ds_read_b128 v[204:207], v195 offset:7168
	global_load_lds_dwordx4 v[192:193], off
	v_lshl_add_u64 v[192:193], s[30:31], 0, v[184:185]
	s_add_i32 m0, s48, 0xe000
	s_nop 0
	global_load_lds_dwordx4 v[192:193], off
	s_waitcnt vmcnt(8)
	s_waitcnt lgkmcnt(0)
	s_barrier
; #define PG8_STAGE(bufoff, gbase, voff) do { _Pragma("unroll") for (int _i = 0; _i < 2; ++_i) \
;         __builtin_amdgcn_global_load_lds((const unsigned*)((const char*)(gbase) + (voff)[_i]), (PG8_LAS unsigned*)(lds + (bufoff) + ldsw + _i * 8192), 16, 0, 0); } while (0)
; #define PG8_LDA(dst, b, h) do { _Pragma("unroll") for (int m = 0; m < 4; ++m) _Pragma("unroll") for (int k = 0; k < 2; ++k) dst[m][k] = *(const PG8_LAS bf16x8*)(lds + PG8_SA(b, h) + aoff + m * 2048 + k * 1024); } while (0)
; #define PG8_MMA(ai, bj, At, Bt) do { __builtin_amdgcn_s_setprio(1); _Pragma("unroll") for (int m = 0; m < 4; ++m) _Pragma("unroll") for (int n = 0; n < 2; ++n) _Pragma("unroll") for (int k = 0; k < 2; ++k) \
;         acc[ai][bj][m][n] = mma16<Epi::F16>(Bt[n][k], At[m][k], acc[ai][bj][m][n]); __builtin_amdgcn_s_setprio(0); } while (0)
; #define PG8_WAIT_V(n) asm volatile("s_waitcnt vmcnt(" #n ")" ::: "memory")
; #define PG8_WAIT_L(n) asm volatile("s_waitcnt lgkmcnt(" #n ")" ::: "memory")
; #define PG8_BAR __builtin_amdgcn_s_barrier()
; #define PG8_SCHED __builtin_amdgcn_sched_barrier(0)
; template <class Epi, class Sched, bool ALIGN_EPI = false, bool SP2 = false>
; __device__ __forceinline__ void gemm_phase(PG8_LAS unsigned char* lds, const Gemm g, const Sched& S, const Epi& E) {
;     ...
;             PG8_WAIT_V(8); PG8_WAIT_L(0); PG8_BAR; PG8_MMA(0, 0, At, B0); PG8_MMA(0, 1, At, B1); PG8_BAR; PG8_SCHED;
;             PG8_LDA(At, 0, 1); PG8_STAGE(PG8_SB(0, 0), b2, voffB); PG8_STAGE(PG8_SB(0, 1), b2 + hstep, voffB); PG8_STAGE(PG8_SA(0, 0), a2, voffA);
;             PG8_WAIT_V(8); PG8_WAIT_L(0); PG8_BAR; PG8_MMA(1, 0, At, B0); PG8_MMA(1, 1, At, B1); PG8_BAR; PG8_SCHED;
	s_setprio 1
	s_waitcnt lgkmcnt(0)
	v_mfma_f32_16x16x32_bf16 v[124:127], v[128:131], v[160:163], 0
	v_mfma_f32_16x16x32_bf16 v[120:123], v[136:139], v[160:163], 0
	v_mfma_f32_16x16x32_bf16 v[108:111], v[128:131], v[168:171], 0
	v_mfma_f32_16x16x32_bf16 v[104:107], v[136:139], v[168:171], 0
	v_mfma_f32_16x16x32_bf16 v[92:95], v[128:131], v[186:189], 0
	v_mfma_f32_16x16x32_bf16 v[88:91], v[136:139], v[186:189], 0
	v_mfma_f32_16x16x32_bf16 v[76:79], v[128:131], v[200:203], 0
	v_mfma_f32_16x16x32_bf16 v[72:75], v[136:139], v[200:203], 0
	v_mfma_f32_16x16x32_bf16 v[124:127], v[132:135], v[164:167], v[124:127]
	v_mfma_f32_16x16x32_bf16 v[120:123], v[140:143], v[164:167], v[120:123]
	v_mfma_f32_16x16x32_bf16 v[108:111], v[132:135], v[172:175], v[108:111]
	v_mfma_f32_16x16x32_bf16 v[104:107], v[140:143], v[172:175], v[104:107]
	v_mfma_f32_16x16x32_bf16 v[92:95], v[132:135], v[196:199], v[92:95]
	v_mfma_f32_16x16x32_bf16 v[88:91], v[140:143], v[196:199], v[88:91]
	v_mfma_f32_16x16x32_bf16 v[76:79], v[132:135], v[204:207], v[76:79]
	v_mfma_f32_16x16x32_bf16 v[72:75], v[140:143], v[204:207], v[72:75]
	s_setprio 0
	s_setprio 1
	v_mfma_f32_16x16x32_bf16 v[116:119], v[144:147], v[160:163], 0
	v_mfma_f32_16x16x32_bf16 v[112:115], v[152:155], v[160:163], 0
	v_mfma_f32_16x16x32_bf16 v[100:103], v[144:147], v[168:171], 0
	v_mfma_f32_16x16x32_bf16 v[96:99], v[152:155], v[168:171], 0
	v_mfma_f32_16x16x32_bf16 v[84:87], v[144:147], v[186:189], 0
	v_mfma_f32_16x16x32_bf16 v[80:83], v[152:155], v[186:189], 0
	v_mfma_f32_16x16x32_bf16 v[68:71], v[144:147], v[200:203], 0
	v_mfma_f32_16x16x32_bf16 v[64:67], v[152:155], v[200:203], 0
	v_mfma_f32_16x16x32_bf16 v[116:119], v[148:151], v[164:167], v[116:119]
	v_mfma_f32_16x16x32_bf16 v[112:115], v[156:159], v[164:167], v[112:115]
	v_mfma_f32_16x16x32_bf16 v[100:103], v[148:151], v[172:175], v[100:103]
	v_mfma_f32_16x16x32_bf16 v[96:99], v[156:159], v[172:175], v[96:99]
	v_mfma_f32_16x16x32_bf16 v[84:87], v[148:151], v[196:199], v[84:87]
	v_mfma_f32_16x16x32_bf16 v[80:83], v[156:159], v[196:199], v[80:83]
	v_mfma_f32_16x16x32_bf16 v[68:71], v[148:151], v[204:207], v[68:71]
	v_mfma_f32_16x16x32_bf16 v[64:67], v[156:159], v[204:207], v[64:67]
	s_setprio 0
	s_barrier
	s_add_i32 s77, s77, s3
	v_lshl_add_u64 v[192:193], s[72:73], 0, v[178:179]
	s_mov_b32 m0, s77
	ds_read_b128 v[160:163], v195 offset:16384
	ds_read_b128 v[164:167], v195 offset:17408
	ds_read_b128 v[168:171], v195 offset:18432
	ds_read_b128 v[172:175], v195 offset:19456
	ds_read_b128 v[186:189], v195 offset:20480
	ds_read_b128 v[196:199], v195 offset:21504
	ds_read_b128 v[200:203], v195 offset:22528
	ds_read_b128 v[204:207], v195 offset:23552
	global_load_lds_dwordx4 v[192:193], off
	s_add_i32 m0, s77, 0x2000
	v_lshl_add_u64 v[212:213], s[72:73], 0, v[176:177]
	s_add_u32 s72, s72, s42
	s_addc_u32 s73, s73, s43
	s_add_i32 s77, s82, s3
	global_load_lds_dwordx4 v[212:213], off
	v_lshl_add_u64 v[214:215], s[72:73], 0, v[178:179]
	s_mov_b32 m0, s77
	v_lshl_add_u64 v[216:217], s[72:73], 0, v[176:177]
	global_load_lds_dwordx4 v[214:215], off
	s_add_i32 m0, s77, 0x2000
	v_lshl_add_u64 v[218:219], s[34:35], 0, v[178:179]
	global_load_lds_dwordx4 v[216:217], off
	s_mov_b32 m0, s48
	v_lshl_add_u64 v[220:221], s[34:35], 0, v[176:177]
	global_load_lds_dwordx4 v[218:219], off
	s_mov_b32 m0, s56
	s_nop 0
	global_load_lds_dwordx4 v[220:221], off
	s_waitcnt vmcnt(8)
	s_waitcnt lgkmcnt(0)
	s_barrier
	s_setprio 1
	s_waitcnt lgkmcnt(0)
	v_mfma_f32_16x16x32_bf16 v[60:63], v[128:131], v[160:163], 0
	v_mfma_f32_16x16x32_bf16 v[56:59], v[136:139], v[160:163], 0
	v_mfma_f32_16x16x32_bf16 v[44:47], v[128:131], v[168:171], 0
	v_mfma_f32_16x16x32_bf16 v[40:43], v[136:139], v[168:171], 0
	v_mfma_f32_16x16x32_bf16 v[28:31], v[128:131], v[186:189], 0
	v_mfma_f32_16x16x32_bf16 v[24:27], v[136:139], v[186:189], 0
	v_mfma_f32_16x16x32_bf16 v[12:15], v[128:131], v[200:203], 0
	v_mfma_f32_16x16x32_bf16 v[8:11], v[136:139], v[200:203], 0
	v_mfma_f32_16x16x32_bf16 v[60:63], v[132:135], v[164:167], v[60:63]
	v_mfma_f32_16x16x32_bf16 v[56:59], v[140:143], v[164:167], v[56:59]
	v_mfma_f32_16x16x32_bf16 v[44:47], v[132:135], v[172:175], v[44:47]
	v_mfma_f32_16x16x32_bf16 v[40:43], v[140:143], v[172:175], v[40:43]
	v_mfma_f32_16x16x32_bf16 v[28:31], v[132:135], v[196:199], v[28:31]
	v_mfma_f32_16x16x32_bf16 v[24:27], v[140:143], v[196:199], v[24:27]
	v_mfma_f32_16x16x32_bf16 v[12:15], v[132:135], v[204:207], v[12:15]
	v_mfma_f32_16x16x32_bf16 v[8:11], v[140:143], v[204:207], v[8:11]
	s_setprio 0
	s_setprio 1
	v_mfma_f32_16x16x32_bf16 v[52:55], v[144:147], v[160:163], 0
	v_mfma_f32_16x16x32_bf16 v[48:51], v[152:155], v[160:163], 0
	v_mfma_f32_16x16x32_bf16 v[36:39], v[144:147], v[168:171], 0
	v_mfma_f32_16x16x32_bf16 v[32:35], v[152:155], v[168:171], 0
	v_mfma_f32_16x16x32_bf16 v[20:23], v[144:147], v[186:189], 0
	v_mfma_f32_16x16x32_bf16 v[16:19], v[152:155], v[186:189], 0
	v_mfma_f32_16x16x32_bf16 v[4:7], v[144:147], v[200:203], 0
	v_mfma_f32_16x16x32_bf16 v[0:3], v[152:155], v[200:203], 0
	v_mfma_f32_16x16x32_bf16 v[52:55], v[148:151], v[164:167], v[52:55]
	v_mfma_f32_16x16x32_bf16 v[48:51], v[156:159], v[164:167], v[48:51]
	v_mfma_f32_16x16x32_bf16 v[36:39], v[148:151], v[172:175], v[36:39]
	v_mfma_f32_16x16x32_bf16 v[32:35], v[156:159], v[172:175], v[32:35]
	v_mfma_f32_16x16x32_bf16 v[20:23], v[148:151], v[196:199], v[20:23]
	v_mfma_f32_16x16x32_bf16 v[16:19], v[156:159], v[196:199], v[16:19]
	v_mfma_f32_16x16x32_bf16 v[4:7], v[148:151], v[204:207], v[4:7]
	v_mfma_f32_16x16x32_bf16 v[0:3], v[156:159], v[204:207], v[0:3]
	s_setprio 0
	s_barrier
; #define PG8_STAGE(bufoff, gbase, voff) do { _Pragma("unroll") for (int _i = 0; _i < 2; ++_i) \
;         __builtin_amdgcn_global_load_lds((const unsigned*)((const char*)(gbase) + (voff)[_i]), (PG8_LAS unsigned*)(lds + (bufoff) + ldsw + _i * 8192), 16, 0, 0); } while (0)
; #define PG8_LDA(dst, b, h) do { _Pragma("unroll") for (int m = 0; m < 4; ++m) _Pragma("unroll") for (int k = 0; k < 2; ++k) dst[m][k] = *(const PG8_LAS bf16x8*)(lds + PG8_SA(b, h) + aoff + m * 2048 + k * 1024); } while (0)
; #define PG8_LDB(dst, b, h) do { _Pragma("unroll") for (int n = 0; n < 2; ++n) _Pragma("unroll") for (int k = 0; k < 2; ++k) dst[n][k] = *(const PG8_LAS bf16x8*)(lds + PG8_SB(b, h) + boff + n * 2048 + k * 1024); } while (0)
; #define PG8_MMA(ai, bj, At, Bt) do { __builtin_amdgcn_s_setprio(1); _Pragma("unroll") for (int m = 0; m < 4; ++m) _Pragma("unroll") for (int n = 0; n < 2; ++n) _Pragma("unroll") for (int k = 0; k < 2; ++k) \
;         acc[ai][bj][m][n] = mma16<Epi::F16>(Bt[n][k], At[m][k], acc[ai][bj][m][n]); __builtin_amdgcn_s_setprio(0); } while (0)
; #define PG8_WAIT_V(n) asm volatile("s_waitcnt vmcnt(" #n ")" ::: "memory")
; #define PG8_WAIT_L(n) asm volatile("s_waitcnt lgkmcnt(" #n ")" ::: "memory")
; #define PG8_BAR __builtin_amdgcn_s_barrier()
; #define PG8_SCHED __builtin_amdgcn_sched_barrier(0)
; template <class Epi, class Sched, bool ALIGN_EPI = false, bool SP2 = false>
; __device__ __forceinline__ void gemm_phase(PG8_LAS unsigned char* lds, const Gemm g, const Sched& S, const Epi& E) {
;     ...
;             PG8_LDB(B0, 1, 0); PG8_LDB(B1, 1, 1); PG8_SCHED; PG8_LDA(At, 1, 0); PG8_STAGE(PG8_SA(0, 1), a2 + hstep, voffA);
;             PG8_WAIT_V(8); PG8_WAIT_L(0); PG8_BAR; PG8_MMA(0, 0, At, B0); PG8_MMA(0, 1, At, B1); PG8_BAR; PG8_SCHED;
	s_add_i32 s72, 0, 0x18000
	s_add_i32 s73, 0, 0x1c000
	v_add_u32_e32 v140, s72, v191
	v_add_u32_e32 v156, s73, v191
	ds_read_b128 v[128:131], v140
	ds_read_b128 v[132:135], v140 offset:1024
	ds_read_b128 v[136:139], v140 offset:2048
	ds_read_b128 v[140:143], v140 offset:3072
	ds_read_b128 v[144:147], v156
	ds_read_b128 v[148:151], v156 offset:1024
	ds_read_b128 v[152:155], v156 offset:2048
	ds_read_b128 v[156:159], v156 offset:3072
	s_add_u32 s34, s34, s42
	s_addc_u32 s35, s35, s43
	s_mov_b32 m0, s57
	v_lshl_add_u64 v[222:223], s[34:35], 0, v[178:179]
	ds_read_b128 v[160:163], v195 offset:32768
	ds_read_b128 v[164:167], v195 offset:33792
	ds_read_b128 v[168:171], v195 offset:34816
	ds_read_b128 v[172:175], v195 offset:35840
	ds_read_b128 v[186:189], v195 offset:36864
	ds_read_b128 v[196:199], v195 offset:37888
	ds_read_b128 v[200:203], v195 offset:38912
	ds_read_b128 v[204:207], v195 offset:39936
	global_load_lds_dwordx4 v[222:223], off
	v_lshl_add_u64 v[222:223], s[34:35], 0, v[176:177]
	s_mov_b32 m0, s59
	s_nop 0
	global_load_lds_dwordx4 v[222:223], off
	s_waitcnt vmcnt(8)
	s_waitcnt lgkmcnt(0)
	s_barrier
	s_setprio 1
	s_waitcnt lgkmcnt(0)
	v_mfma_f32_16x16x32_bf16 v[124:127], v[128:131], v[160:163], v[124:127]
	v_mfma_f32_16x16x32_bf16 v[120:123], v[136:139], v[160:163], v[120:123]
	v_mfma_f32_16x16x32_bf16 v[108:111], v[128:131], v[168:171], v[108:111]
	v_mfma_f32_16x16x32_bf16 v[104:107], v[136:139], v[168:171], v[104:107]
	v_mfma_f32_16x16x32_bf16 v[92:95], v[128:131], v[186:189], v[92:95]
	v_mfma_f32_16x16x32_bf16 v[88:91], v[136:139], v[186:189], v[88:91]
	v_mfma_f32_16x16x32_bf16 v[76:79], v[128:131], v[200:203], v[76:79]
	v_mfma_f32_16x16x32_bf16 v[72:75], v[136:139], v[200:203], v[72:75]
	v_mfma_f32_16x16x32_bf16 v[124:127], v[132:135], v[164:167], v[124:127]
	v_mfma_f32_16x16x32_bf16 v[120:123], v[140:143], v[164:167], v[120:123]
	v_mfma_f32_16x16x32_bf16 v[108:111], v[132:135], v[172:175], v[108:111]
	v_mfma_f32_16x16x32_bf16 v[104:107], v[140:143], v[172:175], v[104:107]
	v_mfma_f32_16x16x32_bf16 v[92:95], v[132:135], v[196:199], v[92:95]
	v_mfma_f32_16x16x32_bf16 v[88:91], v[140:143], v[196:199], v[88:91]
	v_mfma_f32_16x16x32_bf16 v[76:79], v[132:135], v[204:207], v[76:79]
	v_mfma_f32_16x16x32_bf16 v[72:75], v[140:143], v[204:207], v[72:75]
	s_setprio 0
	s_setprio 1
	v_mfma_f32_16x16x32_bf16 v[116:119], v[144:147], v[160:163], v[116:119]
	v_mfma_f32_16x16x32_bf16 v[112:115], v[152:155], v[160:163], v[112:115]
	v_mfma_f32_16x16x32_bf16 v[100:103], v[144:147], v[168:171], v[100:103]
	v_mfma_f32_16x16x32_bf16 v[96:99], v[152:155], v[168:171], v[96:99]
	v_mfma_f32_16x16x32_bf16 v[84:87], v[144:147], v[186:189], v[84:87]
	v_mfma_f32_16x16x32_bf16 v[80:83], v[152:155], v[186:189], v[80:83]
	v_mfma_f32_16x16x32_bf16 v[68:71], v[144:147], v[200:203], v[68:71]
	v_mfma_f32_16x16x32_bf16 v[64:67], v[152:155], v[200:203], v[64:67]
	v_mfma_f32_16x16x32_bf16 v[116:119], v[148:151], v[164:167], v[116:119]
	v_mfma_f32_16x16x32_bf16 v[112:115], v[156:159], v[164:167], v[112:115]
	v_mfma_f32_16x16x32_bf16 v[100:103], v[148:151], v[172:175], v[100:103]
	v_mfma_f32_16x16x32_bf16 v[96:99], v[156:159], v[172:175], v[96:99]
	v_mfma_f32_16x16x32_bf16 v[84:87], v[148:151], v[196:199], v[84:87]
	v_mfma_f32_16x16x32_bf16 v[80:83], v[156:159], v[196:199], v[80:83]
	v_mfma_f32_16x16x32_bf16 v[68:71], v[148:151], v[204:207], v[68:71]
	v_mfma_f32_16x16x32_bf16 v[64:67], v[156:159], v[204:207], v[64:67]
	s_setprio 0
	s_barrier
; #define PG8_STAGE(bufoff, gbase, voff) do { _Pragma("unroll") for (int _i = 0; _i < 2; ++_i) \
;         __builtin_amdgcn_global_load_lds((const unsigned*)((const char*)(gbase) + (voff)[_i]), (PG8_LAS unsigned*)(lds + (bufoff) + ldsw + _i * 8192), 16, 0, 0); } while (0)
; #define PG8_LDA(dst, b, h) do { _Pragma("unroll") for (int m = 0; m < 4; ++m) _Pragma("unroll") for (int k = 0; k < 2; ++k) dst[m][k] = *(const PG8_LAS bf16x8*)(lds + PG8_SA(b, h) + aoff + m * 2048 + k * 1024); } while (0)
; #define PG8_MMA(ai, bj, At, Bt) do { __builtin_amdgcn_s_setprio(1); _Pragma("unroll") for (int m = 0; m < 4; ++m) _Pragma("unroll") for (int n = 0; n < 2; ++n) _Pragma("unroll") for (int k = 0; k < 2; ++k) \
;         acc[ai][bj][m][n] = mma16<Epi::F16>(Bt[n][k], At[m][k], acc[ai][bj][m][n]); __builtin_amdgcn_s_setprio(0); } while (0)
; #define PG8_WAIT_V(n) asm volatile("s_waitcnt vmcnt(" #n ")" ::: "memory")
; #define PG8_WAIT_L(n) asm volatile("s_waitcnt lgkmcnt(" #n ")" ::: "memory")
; #define PG8_BAR __builtin_amdgcn_s_barrier()
; #define PG8_SCHED __builtin_amdgcn_sched_barrier(0)
; template <class Epi, class Sched, bool ALIGN_EPI = false, bool SP2 = false>
; __device__ __forceinline__ void gemm_phase(PG8_LAS unsigned char* lds, const Gemm g, const Sched& S, const Epi& E) {
;     ...
;             PG8_LDA(At, 1, 1); PG8_STAGE(PG8_SB(1, 0), b3, voffB); PG8_STAGE(PG8_SB(1, 1), b3 + hstep, voffB); PG8_STAGE(PG8_SA(1, 0), a3, voffA);
;             PG8_WAIT_V(8); PG8_WAIT_L(0); PG8_BAR; PG8_MMA(1, 0, At, B0); PG8_MMA(1, 1, At, B1); PG8_BAR; PG8_SCHED;
	s_add_i32 s34, s72, s3
	v_lshl_add_u64 v[192:193], v[192:193], 0, s[20:21]
	s_mov_b32 m0, s34
	ds_read_b128 v[160:163], v195 offset:49152
	ds_read_b128 v[164:167], v195 offset:50176
	ds_read_b128 v[168:171], v195 offset:51200
	ds_read_b128 v[172:175], v195 offset:52224
	ds_read_b128 v[186:189], v195 offset:53248
	ds_read_b128 v[196:199], v195 offset:54272
	ds_read_b128 v[200:203], v195 offset:55296
	ds_read_b128 v[204:207], v195 offset:56320
	global_load_lds_dwordx4 v[192:193], off
	v_lshl_add_u64 v[192:193], v[212:213], 0, s[20:21]
	s_add_i32 m0, s34, 0x2000
	s_add_i32 s34, s73, s3
	global_load_lds_dwordx4 v[192:193], off
	v_lshl_add_u64 v[192:193], v[214:215], 0, s[20:21]
	s_mov_b32 m0, s34
	s_nop 0
	global_load_lds_dwordx4 v[192:193], off
	v_lshl_add_u64 v[192:193], v[216:217], 0, s[20:21]
	s_add_i32 m0, s34, 0x2000
	s_nop 0
	global_load_lds_dwordx4 v[192:193], off
	v_lshl_add_u64 v[192:193], v[218:219], 0, s[20:21]
	s_mov_b32 m0, s63
	s_nop 0
	global_load_lds_dwordx4 v[192:193], off
	v_lshl_add_u64 v[192:193], v[220:221], 0, s[20:21]
	s_mov_b32 m0, s64
	s_nop 0
	global_load_lds_dwordx4 v[192:193], off
	s_waitcnt vmcnt(8)
	s_waitcnt lgkmcnt(0)
	s_barrier
	s_setprio 1
	s_waitcnt lgkmcnt(0)
	v_mfma_f32_16x16x32_bf16 v[60:63], v[128:131], v[160:163], v[60:63]
	v_mfma_f32_16x16x32_bf16 v[56:59], v[136:139], v[160:163], v[56:59]
	v_mfma_f32_16x16x32_bf16 v[44:47], v[128:131], v[168:171], v[44:47]
	v_mfma_f32_16x16x32_bf16 v[40:43], v[136:139], v[168:171], v[40:43]
	v_mfma_f32_16x16x32_bf16 v[28:31], v[128:131], v[186:189], v[28:31]
	v_mfma_f32_16x16x32_bf16 v[24:27], v[136:139], v[186:189], v[24:27]
	v_mfma_f32_16x16x32_bf16 v[12:15], v[128:131], v[200:203], v[12:15]
	v_mfma_f32_16x16x32_bf16 v[8:11], v[136:139], v[200:203], v[8:11]
	v_mfma_f32_16x16x32_bf16 v[60:63], v[132:135], v[164:167], v[60:63]
	v_mfma_f32_16x16x32_bf16 v[56:59], v[140:143], v[164:167], v[56:59]
	v_mfma_f32_16x16x32_bf16 v[44:47], v[132:135], v[172:175], v[44:47]
	v_mfma_f32_16x16x32_bf16 v[40:43], v[140:143], v[172:175], v[40:43]
	v_mfma_f32_16x16x32_bf16 v[28:31], v[132:135], v[196:199], v[28:31]
	v_mfma_f32_16x16x32_bf16 v[24:27], v[140:143], v[196:199], v[24:27]
	v_mfma_f32_16x16x32_bf16 v[12:15], v[132:135], v[204:207], v[12:15]
	v_mfma_f32_16x16x32_bf16 v[8:11], v[140:143], v[204:207], v[8:11]
	s_setprio 0
	s_setprio 1
	v_mfma_f32_16x16x32_bf16 v[52:55], v[144:147], v[160:163], v[52:55]
	v_mfma_f32_16x16x32_bf16 v[48:51], v[152:155], v[160:163], v[48:51]
	v_mfma_f32_16x16x32_bf16 v[36:39], v[144:147], v[168:171], v[36:39]
	v_mfma_f32_16x16x32_bf16 v[32:35], v[152:155], v[168:171], v[32:35]
	v_mfma_f32_16x16x32_bf16 v[20:23], v[144:147], v[186:189], v[20:23]
	v_mfma_f32_16x16x32_bf16 v[16:19], v[152:155], v[186:189], v[16:19]
	v_mfma_f32_16x16x32_bf16 v[4:7], v[144:147], v[200:203], v[4:7]
	v_mfma_f32_16x16x32_bf16 v[0:3], v[152:155], v[200:203], v[0:3]
	v_mfma_f32_16x16x32_bf16 v[52:55], v[148:151], v[164:167], v[52:55]
	v_mfma_f32_16x16x32_bf16 v[48:51], v[156:159], v[164:167], v[48:51]
	v_mfma_f32_16x16x32_bf16 v[36:39], v[148:151], v[172:175], v[36:39]
	v_mfma_f32_16x16x32_bf16 v[32:35], v[156:159], v[172:175], v[32:35]
	v_mfma_f32_16x16x32_bf16 v[20:23], v[148:151], v[196:199], v[20:23]
	v_mfma_f32_16x16x32_bf16 v[16:19], v[156:159], v[196:199], v[16:19]
	v_mfma_f32_16x16x32_bf16 v[4:7], v[148:151], v[204:207], v[4:7]
	v_mfma_f32_16x16x32_bf16 v[0:3], v[156:159], v[204:207], v[0:3]
	s_setprio 0
	s_barrier
	s_add_u32 s30, s30, 0x100
	s_addc_u32 s31, s31, 0
	s_add_u32 s69, s69, 0x100
	s_addc_u32 s70, s70, 0
	s_cmp_ge_i32 s71, s60
	s_mov_b32 s34, s71
	s_cbranch_scc0 .LBB0_1147
	s_branch .LBB0_1148

; template <int NP> __device__ __forceinline__ void load_rstd8(const float* ss, const Unit& u, int wr, int fr, int fq, float inv_n, float (&rs)[2][4]) {
;     f32x4 v[2][4];
; #pragma unroll
;     for (int ai = 0; ai < 2; ++ai)
; #pragma unroll
;         for (int m = 0; m < 4; ++m) { const int row = u.pm * BM + ai * HALF + wr * 64 + m * 16 + fr; v[ai][m] = *(const f32x4*)(ss + (size_t)row * NP + (NP == 16 ? 4 * fq : 0)); }
; #pragma unroll
;     for (int ai = 0; ai < 2; ++ai)
; #pragma unroll
;         for (int m = 0; m < 4; ++m) { float t = (v[ai][m][0] + v[ai][m][1]) + (v[ai][m][2] + v[ai][m][3]); if (NP == 16) t = quad_sum(t); rs[ai][m] = __builtin_amdgcn_rsqf(t * inv_n + kEps); }
; }
;     __device__ __forceinline__ void operator()(const f32x4 (&acc)[2][2][4][2], const Unit& u, int wr, int wc, int fr, int fq) const {
;         float rsv[2][4]; load_rstd8<4>(ssq, u, wr, fr, fq, 1.0f / 256.0f, rsv);
;         f32x4 rc[2][4], rsn[2][4];
; #pragma unroll
;         for (int ai = 0; ai < 2; ++ai)
; #pragma unroll
;             for (int m = 0; m < 4; ++m) { const int pos = (u.pm * BM + ai * HALF + wr * 64 + m * 16 + fr) & 2047;
;                 rc[ai][m] = *(const f32x4*)(rope + pos * 32 + fq * 4); rsn[ai][m] = *(const f32x4*)(rope + pos * 32 + 16 + fq * 4); }
; #pragma unroll
;         for (int ai = 0; ai < 2; ++ai)
; #pragma unroll
;             for (int m = 0; m < 4; ++m) {
;                 const int row = u.pm * BM + ai * HALF + wr * 64 + m * 16 + fr;
;                 const float rs = rsv[ai][m];
; #pragma unroll
;                 for (int bj = 0; bj < 2; ++bj) {
;                     const int cb = u.pn * BM + bj * HALF + wc * 32;
;                     f32x4 x1 = acc[ai][bj][m][0] * rs, x2 = acc[ai][bj][m][1] * rs;
;                     if ((cb % 96) == 64) { const f32x4 c = rc[ai][m], sn = rsn[ai][m]; const f32x4 y1 = x1 * c - x2 * sn, y2 = x1 * sn + x2 * c; x1 = y1; x2 = y2; }
.LBB0_1150:
	s_lshl_b32 s30, s41, 8
	s_add_i32 s30, s30, s61
	v_or_b32_e32 v216, s30, v181
	v_readlane_b32 s34, v252, 42
	v_or_b32_e32 v212, 16, v216
	v_ashrrev_i32_e32 v217, 31, v216
	v_readlane_b32 s35, v252, 43
	v_ashrrev_i32_e32 v213, 31, v212
	v_or_b32_e32 v204, 32, v216
	v_or_b32_e32 v200, 48, v216
	v_add_u32_e32 v196, 0x80, v216
	v_add_u32_e32 v192, 0x90, v216
	v_add_u32_e32 v188, 0xa0, v216
	v_lshl_add_u64 v[128:129], v[216:217], 4, s[34:35]
	v_lshl_add_u64 v[132:133], v[212:213], 4, s[34:35]
	v_ashrrev_i32_e32 v205, 31, v204
	v_ashrrev_i32_e32 v201, 31, v200
	v_ashrrev_i32_e32 v197, 31, v196
	v_ashrrev_i32_e32 v193, 31, v192
	v_ashrrev_i32_e32 v189, 31, v188
	global_load_dwordx4 v[128:131], v[128:129], off
	s_nop 0
	global_load_dwordx4 v[132:135], v[132:133], off
	v_lshl_add_u64 v[136:137], v[204:205], 4, s[34:35]
	v_lshl_add_u64 v[140:141], v[200:201], 4, s[34:35]
	v_lshl_add_u64 v[144:145], v[196:197], 4, s[34:35]
	v_lshl_add_u64 v[148:149], v[192:193], 4, s[34:35]
	v_lshl_add_u64 v[152:153], v[188:189], 4, s[34:35]
	global_load_dwordx4 v[136:139], v[136:137], off
	s_nop 0
	global_load_dwordx4 v[140:143], v[140:141], off
	v_add_u32_e32 v186, 0xb0, v216
	global_load_dwordx4 v[144:147], v[144:145], off
	v_ashrrev_i32_e32 v187, 31, v186
	global_load_dwordx4 v[148:151], v[148:149], off
	v_lshl_add_u64 v[156:157], v[186:187], 4, s[34:35]
	global_load_dwordx4 v[152:155], v[152:153], off
	s_and_b32 s31, s30, 0x7c0
	global_load_dwordx4 v[156:159], v[156:157], off
	v_or_b32_e32 v160, s31, v181
	v_readlane_b32 s34, v254, 53
	v_lshlrev_b32_e32 v208, 7, v160
	v_readlane_b32 s35, v254, 54
	s_movk_i32 s10, 0x1000
	s_addk_i32 s30, 0x80
	v_lshl_add_u64 v[160:161], s[34:35], 0, v[208:209]
	v_lshlrev_b32_e32 v208, 2, v180
	v_lshl_add_u64 v[160:161], v[160:161], 0, v[208:209]
	global_load_dwordx4 v[218:221], v[160:161], off
	global_load_dwordx4 v[222:225], v[160:161], off offset:64
	global_load_dwordx4 v[226:229], v[160:161], off offset:2048
	global_load_dwordx4 v[230:233], v[160:161], off offset:2112
	s_and_b32 s30, s30, 0x7c0
	s_waitcnt vmcnt(0)
	v_mov_b32_e32 v162, v129
	v_mov_b32_e32 v163, v130
	v_mov_b32_e32 v129, v131
	v_pk_add_f32 v[128:129], v[162:163], v[128:129]
	v_mov_b32_e32 v130, v133
	v_mov_b32_e32 v131, v134
	v_mov_b32_e32 v133, v135
	v_mov_b32_e32 v134, v137
	v_mov_b32_e32 v135, v138
	v_mov_b32_e32 v137, v139
	v_mov_b32_e32 v138, v141
	v_mov_b32_e32 v141, v143
	v_mov_b32_e32 v143, v146
	v_mov_b32_e32 v146, v149
	v_mov_b32_e32 v149, v151
	v_mov_b32_e32 v151, v154
	v_add_f32_e32 v154, v128, v129
	v_pk_add_f32 v[128:129], v[130:131], v[132:133]
	v_pk_add_f32 v[130:131], v[134:135], v[136:137]
	v_add_f32_e32 v128, v128, v129
	v_add_f32_e32 v129, v130, v131
	v_fmamk_f32 v128, v128, 0x3b800000, v240
	v_fmamk_f32 v129, v129, 0x3b800000, v240
	v_rsq_f32_e32 v236, v128
	v_rsq_f32_e32 v214, v129
	v_mov_b32_e32 v128, v157
	v_mov_b32_e32 v129, v158
	v_mov_b32_e32 v157, v159
	v_pk_add_f32 v[128:129], v[128:129], v[156:157]
	v_mov_b32_e32 v139, v142
	v_add_f32_e32 v128, v128, v129
	v_fmamk_f32 v128, v128, 0x3b800000, v240
	v_rsq_f32_e32 v190, v128
	v_add_co_u32_e32 v128, vcc, s10, v160
	v_mov_b32_e32 v142, v145
	s_nop 0
	v_addc_co_u32_e32 v129, vcc, 0, v161, vcc
	global_load_dwordx4 v[168:171], v[128:129], off
	global_load_dwordx4 v[172:175], v[128:129], off offset:64
	global_load_dwordx4 v[160:163], v[128:129], off offset:2048
	global_load_dwordx4 v[164:167], v[128:129], off offset:2112
	v_or_b32_e32 v128, s30, v181
	v_lshlrev_b32_e32 v128, 7, v128
	v_mov_b32_e32 v129, v209
	v_lshl_add_u64 v[128:129], s[34:35], 0, v[128:129]
	v_mov_b32_e32 v145, v147
	v_mov_b32_e32 v147, v150
	v_mov_b32_e32 v150, v153
	v_mov_b32_e32 v153, v155
	v_lshl_add_u64 v[128:129], v[128:129], 0, v[208:209]
	v_pk_add_f32 v[132:133], v[138:139], v[140:141]
	v_pk_add_f32 v[134:135], v[142:143], v[144:145]
	v_pk_add_f32 v[136:137], v[146:147], v[148:149]
	v_pk_add_f32 v[138:139], v[150:151], v[152:153]
	v_fmamk_f32 v140, v154, 0x3b800000, v240
	global_load_dwordx4 v[152:155], v[128:129], off
	global_load_dwordx4 v[156:159], v[128:129], off offset:64
	global_load_dwordx4 v[144:147], v[128:129], off offset:2048
	global_load_dwordx4 v[148:151], v[128:129], off offset:2112
	v_add_f32_e32 v130, v132, v133
	v_add_f32_e32 v132, v136, v137
	v_add_f32_e32 v133, v138, v139
	v_fmamk_f32 v132, v132, 0x3b800000, v240
	v_add_f32_e32 v131, v134, v135
	v_fmamk_f32 v133, v133, 0x3b800000, v240
	v_rsq_f32_e32 v198, v132
	v_add_co_u32_e32 v132, vcc, s10, v128
	v_fmamk_f32 v130, v130, 0x3b800000, v240
	v_fmamk_f32 v131, v131, 0x3b800000, v240
	v_rsq_f32_e32 v194, v133
	v_addc_co_u32_e32 v133, vcc, 0, v129, vcc
	v_rsq_f32_e32 v234, v140
	v_rsq_f32_e32 v206, v130
	v_rsq_f32_e32 v202, v131
	global_load_dwordx4 v[136:139], v[132:133], off
	global_load_dwordx4 v[140:143], v[132:133], off offset:64
	global_load_dwordx4 v[128:131], v[132:133], off offset:2048
	s_nop 0
	global_load_dwordx4 v[132:135], v[132:133], off offset:2112
	s_lshl_b32 s30, s40, 8
	s_or_b32 s34, s30, s62
	s_mul_hi_i32 s30, s34, 0x2aaaaaab
	s_lshr_b32 s31, s30, 31
	s_lshr_b32 s30, s30, 4
	s_add_i32 s30, s30, s31
	s_mulk_i32 s30, 0x60
	v_pk_mul_f32 v[120:121], v[120:121], v[234:235] op_sel_hi:[1,0]
	s_sub_i32 s30, s34, s30
	v_pk_mul_f32 v[124:125], v[124:125], v[234:235] op_sel_hi:[1,0]
	v_pk_mul_f32 v[122:123], v[122:123], v[234:235] op_sel_hi:[1,0]
	s_cmp_eq_u32 s30, 64
	v_pk_mul_f32 v[250:251], v[218:219], v[120:121]
	v_readlane_b32 s30, v254, 30
	v_pk_mul_f32 v[126:127], v[126:127], v[234:235] op_sel_hi:[1,0]
	v_pk_mul_f32 v[248:249], v[220:221], v[122:123]
	v_pk_fma_f32 v[250:251], v[222:223], v[124:125], v[250:251]
; __device__ __forceinline__ u32x2 pack4(const f32x4 v) { u32x2 w; w.x = cvt_pk_bf16(v[0], v[1]); w.y = cvt_pk_bf16(v[2], v[3]); return w; }
;     __device__ __forceinline__ void operator()(const f32x4 (&acc)[2][2][4][2], const Unit& u, int wr, int wc, int fr, int fq) const {
;     ...
;                 const int row = u.pm * BM + ai * HALF + wr * 64 + m * 16 + fr;
;                 const float rs = rsv[ai][m];
; #pragma unroll
;                 for (int bj = 0; bj < 2; ++bj) {
;                     const int cb = u.pn * BM + bj * HALF + wc * 32;
;                     f32x4 x1 = acc[ai][bj][m][0] * rs, x2 = acc[ai][bj][m][1] * rs;
;                     if ((cb % 96) == 64) { const f32x4 c = rc[ai][m], sn = rsn[ai][m]; const f32x4 y1 = x1 * c - x2 * sn, y2 = x1 * sn + x2 * c; x1 = y1; x2 = y2; }
;                     bf16_t* qp = Q + (size_t)row * 768 + cb + fq * 4; *(u32x2*)qp = pack4(x1); *(u32x2*)(qp + 16) = pack4(x2);
;                 }
	s_cselect_b64 vcc, -1, 0
	v_readlane_b32 s31, v254, 31
	v_pk_mul_f32 v[246:247], v[222:223], v[120:121]
	v_pk_fma_f32 v[248:249], v[224:225], v[126:127], v[248:249]
	v_cndmask_b32_e32 v193, v120, v250, vcc
	v_cndmask_b32_e32 v197, v121, v251, vcc
	v_mov_b64_e32 v[120:121], s[30:31]
	v_pk_mul_f32 v[244:245], v[224:225], v[122:123]
	v_cndmask_b32_e32 v187, v122, v248, vcc
	v_cndmask_b32_e32 v189, v123, v249, vcc
	v_mad_i64_i32 v[122:123], s[30:31], v216, s83, v[120:121]
	s_ashr_i32 s35, s34, 31
	s_lshl_b64 s[30:31], s[34:35], 1
	s_bitset1_b32 s34, 7
	s_mul_hi_i32 s35, s34, 0x2aaaaaab
	v_pk_fma_f32 v[246:247], v[218:219], v[124:125], v[246:247] neg_lo:[0,0,1] neg_hi:[0,0,1]
	s_lshr_b32 s40, s35, 31
	s_lshr_b32 s35, s35, 4
	v_pk_fma_f32 v[244:245], v[220:221], v[126:127], v[244:245] neg_lo:[0,0,1] neg_hi:[0,0,1]
	v_cndmask_b32_e32 v124, v124, v246, vcc
	v_cndmask_b32_e32 v125, v125, v247, vcc
	v_lshl_add_u64 v[122:123], v[122:123], 0, s[30:31]
	v_lshlrev_b32_e32 v208, 1, v180
	s_add_i32 s35, s35, s40
	v_cndmask_b32_e32 v126, v126, v244, vcc
	v_cndmask_b32_e32 v127, v127, v245, vcc
	v_lshl_add_u64 v[122:123], v[122:123], 0, v[208:209]
	v_cvt_pk_bf16_f32 v124, v124, v125
	v_cvt_pk_bf16_f32 v125, v126, v127
	v_pk_mul_f32 v[112:113], v[112:113], v[234:235] op_sel_hi:[1,0]
	s_mulk_i32 s35, 0x60
	global_store_dwordx2 v[122:123], v[124:125], off
	v_cvt_pk_bf16_f32 v124, v193, v197
	v_cvt_pk_bf16_f32 v125, v187, v189
	v_pk_mul_f32 v[116:117], v[116:117], v[234:235] op_sel_hi:[1,0]
	v_pk_mul_f32 v[114:115], v[114:115], v[234:235] op_sel_hi:[1,0]
	s_sub_i32 s34, s34, s35
	v_pk_mul_f32 v[126:127], v[222:223], v[112:113]
	global_store_dwordx2 v[122:123], v[124:125], off offset:32
	v_pk_mul_f32 v[118:119], v[118:119], v[234:235] op_sel_hi:[1,0]
	s_cmp_eq_u32 s34, 64
	v_pk_mul_f32 v[124:125], v[224:225], v[114:115]
	v_pk_fma_f32 v[126:127], v[218:219], v[116:117], v[126:127] neg_lo:[0,0,1] neg_hi:[0,0,1]
	v_pk_mul_f32 v[216:217], v[220:221], v[114:115]
	v_pk_mul_f32 v[218:219], v[218:219], v[112:113]
	v_pk_fma_f32 v[124:125], v[220:221], v[118:119], v[124:125] neg_lo:[0,0,1] neg_hi:[0,0,1]
	v_pk_fma_f32 v[218:219], v[222:223], v[116:117], v[218:219]
	v_pk_fma_f32 v[216:217], v[224:225], v[118:119], v[216:217]
	s_cselect_b64 s[40:41], -1, 0
	v_cndmask_b32_e64 v118, v118, v124, s[40:41]
	v_cndmask_b32_e64 v119, v119, v125, s[40:41]
	v_cndmask_b32_e64 v116, v116, v126, s[40:41]
	v_cndmask_b32_e64 v117, v117, v127, s[40:41]
	v_cndmask_b32_e64 v114, v114, v216, s[40:41]
	v_cndmask_b32_e64 v115, v115, v217, s[40:41]
	v_cndmask_b32_e64 v124, v112, v218, s[40:41]
	v_cndmask_b32_e64 v125, v113, v219, s[40:41]
	v_cvt_pk_bf16_f32 v112, v116, v117
	v_cvt_pk_bf16_f32 v113, v118, v119
	v_pk_mul_f32 v[108:109], v[108:109], v[236:237] op_sel_hi:[1,0]
	v_pk_mul_f32 v[104:105], v[104:105], v[236:237] op_sel_hi:[1,0]
	global_store_dwordx2 v[122:123], v[112:113], off offset:256
	v_cvt_pk_bf16_f32 v112, v124, v125
	v_cvt_pk_bf16_f32 v113, v114, v115
	v_pk_mul_f32 v[114:115], v[104:105], v[230:231]
	v_pk_mul_f32 v[118:119], v[108:109], v[230:231]
	v_pk_mul_f32 v[110:111], v[110:111], v[236:237] op_sel_hi:[1,0]
	v_pk_mul_f32 v[106:107], v[106:107], v[236:237] op_sel_hi:[1,0]
	v_pk_fma_f32 v[114:115], v[226:227], v[108:109], v[114:115] neg_lo:[0,0,1] neg_hi:[0,0,1]
	v_pk_fma_f32 v[118:119], v[226:227], v[104:105], v[118:119]
	global_store_dwordx2 v[122:123], v[112:113], off offset:288
	v_pk_mul_f32 v[112:113], v[106:107], v[232:233]
	v_pk_mul_f32 v[116:117], v[110:111], v[232:233]
	v_cndmask_b32_e32 v108, v108, v114, vcc
	v_cndmask_b32_e32 v109, v109, v115, vcc
	v_cndmask_b32_e32 v114, v104, v118, vcc
	v_cndmask_b32_e32 v115, v105, v119, vcc
	v_mad_i64_i32 v[104:105], s[34:35], v212, s83, v[120:121]
	v_pk_fma_f32 v[112:113], v[228:229], v[110:111], v[112:113] neg_lo:[0,0,1] neg_hi:[0,0,1]
	v_pk_fma_f32 v[116:117], v[228:229], v[106:107], v[116:117]
	v_lshl_add_u64 v[104:105], v[104:105], 0, s[30:31]
	v_cndmask_b32_e32 v110, v110, v112, vcc
	v_cndmask_b32_e32 v111, v111, v113, vcc
	v_cndmask_b32_e32 v112, v106, v116, vcc
	v_cndmask_b32_e32 v113, v107, v117, vcc
	v_lshl_add_u64 v[104:105], v[104:105], 0, v[208:209]
	v_cvt_pk_bf16_f32 v106, v108, v109
	v_cvt_pk_bf16_f32 v107, v110, v111
	global_store_dwordx2 v[104:105], v[106:107], off
	v_cvt_pk_bf16_f32 v106, v114, v115
	v_cvt_pk_bf16_f32 v107, v112, v113
	v_pk_mul_f32 v[100:101], v[100:101], v[236:237] op_sel_hi:[1,0]
	v_pk_mul_f32 v[102:103], v[102:103], v[236:237] op_sel_hi:[1,0]
	v_pk_mul_f32 v[96:97], v[96:97], v[236:237] op_sel_hi:[1,0]
	v_pk_mul_f32 v[98:99], v[98:99], v[236:237] op_sel_hi:[1,0]
	global_store_dwordx2 v[104:105], v[106:107], off offset:32
	v_pk_mul_f32 v[106:107], v[98:99], v[232:233]
	v_pk_mul_f32 v[108:109], v[96:97], v[230:231]
	v_pk_mul_f32 v[110:111], v[102:103], v[232:233]
	v_pk_mul_f32 v[112:113], v[100:101], v[230:231]
	v_pk_fma_f32 v[108:109], v[226:227], v[100:101], v[108:109] neg_lo:[0,0,1] neg_hi:[0,0,1]
	v_pk_fma_f32 v[106:107], v[228:229], v[102:103], v[106:107] neg_lo:[0,0,1] neg_hi:[0,0,1]
	v_pk_fma_f32 v[112:113], v[226:227], v[96:97], v[112:113]
	v_pk_fma_f32 v[110:111], v[228:229], v[98:99], v[110:111]
	v_cndmask_b32_e64 v102, v102, v106, s[40:41]
	v_cndmask_b32_e64 v103, v103, v107, s[40:41]
	v_cndmask_b32_e64 v100, v100, v108, s[40:41]
	v_cndmask_b32_e64 v101, v101, v109, s[40:41]
	v_cndmask_b32_e64 v98, v98, v110, s[40:41]
	v_cndmask_b32_e64 v99, v99, v111, s[40:41]
	v_cndmask_b32_e64 v106, v96, v112, s[40:41]
	v_cndmask_b32_e64 v107, v97, v113, s[40:41]
	v_cvt_pk_bf16_f32 v96, v100, v101
	v_cvt_pk_bf16_f32 v97, v102, v103
	v_pk_mul_f32 v[92:93], v[92:93], v[214:215] op_sel_hi:[1,0]
	v_pk_mul_f32 v[88:89], v[88:89], v[214:215] op_sel_hi:[1,0]
	global_store_dwordx2 v[104:105], v[96:97], off offset:256
	v_cvt_pk_bf16_f32 v96, v106, v107
	v_cvt_pk_bf16_f32 v97, v98, v99
	s_waitcnt vmcnt(0)
; __device__ __forceinline__ u32x2 pack4(const f32x4 v) { u32x2 w; w.x = cvt_pk_bf16(v[0], v[1]); w.y = cvt_pk_bf16(v[2], v[3]); return w; }
;     __device__ __forceinline__ void operator()(const f32x4 (&acc)[2][2][4][2], const Unit& u, int wr, int wc, int fr, int fq) const {
;     ...
;                 const int row = u.pm * BM + ai * HALF + wr * 64 + m * 16 + fr;
;                 const float rs = rsv[ai][m];
; #pragma unroll
;                 for (int bj = 0; bj < 2; ++bj) {
;                     const int cb = u.pn * BM + bj * HALF + wc * 32;
;                     f32x4 x1 = acc[ai][bj][m][0] * rs, x2 = acc[ai][bj][m][1] * rs;
;                     if ((cb % 96) == 64) { const f32x4 c = rc[ai][m], sn = rsn[ai][m]; const f32x4 y1 = x1 * c - x2 * sn, y2 = x1 * sn + x2 * c; x1 = y1; x2 = y2; }
;                     bf16_t* qp = Q + (size_t)row * 768 + cb + fq * 4; *(u32x2*)qp = pack4(x1); *(u32x2*)(qp + 16) = pack4(x2);
;                 }
	v_pk_mul_f32 v[98:99], v[88:89], v[172:173]
	v_pk_mul_f32 v[102:103], v[92:93], v[172:173]
	v_pk_mul_f32 v[94:95], v[94:95], v[214:215] op_sel_hi:[1,0]
	v_pk_mul_f32 v[90:91], v[90:91], v[214:215] op_sel_hi:[1,0]
	v_pk_fma_f32 v[98:99], v[92:93], v[168:169], v[98:99] neg_lo:[0,0,1] neg_hi:[0,0,1]
	v_pk_fma_f32 v[102:103], v[88:89], v[168:169], v[102:103]
	global_store_dwordx2 v[104:105], v[96:97], off offset:288
	v_pk_mul_f32 v[96:97], v[90:91], v[174:175]
	v_pk_mul_f32 v[100:101], v[94:95], v[174:175]
	v_cndmask_b32_e32 v92, v92, v98, vcc
	v_cndmask_b32_e32 v93, v93, v99, vcc
	v_cndmask_b32_e32 v98, v88, v102, vcc
	v_cndmask_b32_e32 v99, v89, v103, vcc
	v_mad_i64_i32 v[88:89], s[34:35], v204, s83, v[120:121]
	v_pk_fma_f32 v[96:97], v[94:95], v[170:171], v[96:97] neg_lo:[0,0,1] neg_hi:[0,0,1]
	v_pk_fma_f32 v[100:101], v[90:91], v[170:171], v[100:101]
	v_lshl_add_u64 v[88:89], v[88:89], 0, s[30:31]
	v_cndmask_b32_e32 v94, v94, v96, vcc
	v_cndmask_b32_e32 v95, v95, v97, vcc
	v_cndmask_b32_e32 v96, v90, v100, vcc
	v_cndmask_b32_e32 v97, v91, v101, vcc
	v_lshl_add_u64 v[88:89], v[88:89], 0, v[208:209]
	v_cvt_pk_bf16_f32 v90, v92, v93
	v_cvt_pk_bf16_f32 v91, v94, v95
	global_store_dwordx2 v[88:89], v[90:91], off
	v_cvt_pk_bf16_f32 v90, v98, v99
	v_cvt_pk_bf16_f32 v91, v96, v97
	v_pk_mul_f32 v[84:85], v[84:85], v[214:215] op_sel_hi:[1,0]
	v_pk_mul_f32 v[86:87], v[86:87], v[214:215] op_sel_hi:[1,0]
	v_pk_mul_f32 v[80:81], v[80:81], v[214:215] op_sel_hi:[1,0]
	v_pk_mul_f32 v[82:83], v[82:83], v[214:215] op_sel_hi:[1,0]
	global_store_dwordx2 v[88:89], v[90:91], off offset:32
	v_pk_mul_f32 v[90:91], v[82:83], v[174:175]
	v_pk_mul_f32 v[92:93], v[80:81], v[172:173]
	v_pk_mul_f32 v[94:95], v[86:87], v[174:175]
	v_pk_mul_f32 v[96:97], v[84:85], v[172:173]
	v_pk_fma_f32 v[92:93], v[84:85], v[168:169], v[92:93] neg_lo:[0,0,1] neg_hi:[0,0,1]
	v_pk_fma_f32 v[90:91], v[86:87], v[170:171], v[90:91] neg_lo:[0,0,1] neg_hi:[0,0,1]
	v_pk_fma_f32 v[96:97], v[80:81], v[168:169], v[96:97]
	v_pk_fma_f32 v[94:95], v[82:83], v[170:171], v[94:95]
	v_cndmask_b32_e64 v86, v86, v90, s[40:41]
	v_cndmask_b32_e64 v87, v87, v91, s[40:41]
	v_cndmask_b32_e64 v84, v84, v92, s[40:41]
	v_cndmask_b32_e64 v85, v85, v93, s[40:41]
	v_cndmask_b32_e64 v82, v82, v94, s[40:41]
	v_cndmask_b32_e64 v83, v83, v95, s[40:41]
	v_cndmask_b32_e64 v90, v80, v96, s[40:41]
	v_cndmask_b32_e64 v91, v81, v97, s[40:41]
	v_cvt_pk_bf16_f32 v80, v84, v85
	v_cvt_pk_bf16_f32 v81, v86, v87
	v_pk_mul_f32 v[76:77], v[76:77], v[206:207] op_sel_hi:[1,0]
	v_pk_mul_f32 v[72:73], v[72:73], v[206:207] op_sel_hi:[1,0]
	global_store_dwordx2 v[88:89], v[80:81], off offset:256
	v_cvt_pk_bf16_f32 v80, v90, v91
	v_cvt_pk_bf16_f32 v81, v82, v83
	v_pk_mul_f32 v[82:83], v[72:73], v[164:165]
	v_pk_mul_f32 v[86:87], v[76:77], v[164:165]
	v_pk_mul_f32 v[78:79], v[78:79], v[206:207] op_sel_hi:[1,0]
	v_pk_mul_f32 v[74:75], v[74:75], v[206:207] op_sel_hi:[1,0]
	v_pk_fma_f32 v[82:83], v[76:77], v[160:161], v[82:83] neg_lo:[0,0,1] neg_hi:[0,0,1]
	v_pk_fma_f32 v[86:87], v[72:73], v[160:161], v[86:87]
	global_store_dwordx2 v[88:89], v[80:81], off offset:288
	v_pk_mul_f32 v[80:81], v[74:75], v[166:167]
	v_pk_mul_f32 v[84:85], v[78:79], v[166:167]
	v_cndmask_b32_e32 v76, v76, v82, vcc
	v_cndmask_b32_e32 v77, v77, v83, vcc
	v_cndmask_b32_e32 v82, v72, v86, vcc
	v_cndmask_b32_e32 v83, v73, v87, vcc
	v_mad_i64_i32 v[72:73], s[34:35], v200, s83, v[120:121]
	v_pk_fma_f32 v[80:81], v[78:79], v[162:163], v[80:81] neg_lo:[0,0,1] neg_hi:[0,0,1]
	v_pk_fma_f32 v[84:85], v[74:75], v[162:163], v[84:85]
	v_lshl_add_u64 v[72:73], v[72:73], 0, s[30:31]
	v_cndmask_b32_e32 v78, v78, v80, vcc
	v_cndmask_b32_e32 v79, v79, v81, vcc
	v_cndmask_b32_e32 v80, v74, v84, vcc
	v_cndmask_b32_e32 v81, v75, v85, vcc
	v_lshl_add_u64 v[72:73], v[72:73], 0, v[208:209]
	v_cvt_pk_bf16_f32 v74, v76, v77
	v_cvt_pk_bf16_f32 v75, v78, v79
	global_store_dwordx2 v[72:73], v[74:75], off
	v_cvt_pk_bf16_f32 v74, v82, v83
	v_cvt_pk_bf16_f32 v75, v80, v81
	v_pk_mul_f32 v[68:69], v[68:69], v[206:207] op_sel_hi:[1,0]
	v_pk_mul_f32 v[70:71], v[70:71], v[206:207] op_sel_hi:[1,0]
	v_pk_mul_f32 v[64:65], v[64:65], v[206:207] op_sel_hi:[1,0]
	v_pk_mul_f32 v[66:67], v[66:67], v[206:207] op_sel_hi:[1,0]
	global_store_dwordx2 v[72:73], v[74:75], off offset:32
	v_pk_mul_f32 v[74:75], v[66:67], v[166:167]
	v_pk_mul_f32 v[76:77], v[64:65], v[164:165]
	v_pk_mul_f32 v[78:79], v[70:71], v[166:167]
	v_pk_mul_f32 v[80:81], v[68:69], v[164:165]
	v_pk_fma_f32 v[76:77], v[68:69], v[160:161], v[76:77] neg_lo:[0,0,1] neg_hi:[0,0,1]
	v_pk_fma_f32 v[74:75], v[70:71], v[162:163], v[74:75] neg_lo:[0,0,1] neg_hi:[0,0,1]
	v_pk_fma_f32 v[80:81], v[64:65], v[160:161], v[80:81]
	v_pk_fma_f32 v[78:79], v[66:67], v[162:163], v[78:79]
	v_cndmask_b32_e64 v70, v70, v74, s[40:41]
	v_cndmask_b32_e64 v71, v71, v75, s[40:41]
	v_cndmask_b32_e64 v68, v68, v76, s[40:41]
	v_cndmask_b32_e64 v69, v69, v77, s[40:41]
	v_cndmask_b32_e64 v66, v66, v78, s[40:41]
	v_cndmask_b32_e64 v67, v67, v79, s[40:41]
	v_cndmask_b32_e64 v74, v64, v80, s[40:41]
	v_cndmask_b32_e64 v75, v65, v81, s[40:41]
	v_cvt_pk_bf16_f32 v64, v68, v69
	v_cvt_pk_bf16_f32 v65, v70, v71
	v_pk_mul_f32 v[60:61], v[60:61], v[202:203] op_sel_hi:[1,0]
	v_pk_mul_f32 v[56:57], v[56:57], v[202:203] op_sel_hi:[1,0]
	global_store_dwordx2 v[72:73], v[64:65], off offset:256
	v_cvt_pk_bf16_f32 v64, v74, v75
	v_cvt_pk_bf16_f32 v65, v66, v67
	v_pk_mul_f32 v[66:67], v[56:57], v[156:157]
	v_pk_mul_f32 v[70:71], v[60:61], v[156:157]
	v_pk_mul_f32 v[62:63], v[62:63], v[202:203] op_sel_hi:[1,0]
	v_pk_mul_f32 v[58:59], v[58:59], v[202:203] op_sel_hi:[1,0]
; __device__ __forceinline__ u32x2 pack4(const f32x4 v) { u32x2 w; w.x = cvt_pk_bf16(v[0], v[1]); w.y = cvt_pk_bf16(v[2], v[3]); return w; }
;     __device__ __forceinline__ void operator()(const f32x4 (&acc)[2][2][4][2], const Unit& u, int wr, int wc, int fr, int fq) const {
;     ...
;                 const int row = u.pm * BM + ai * HALF + wr * 64 + m * 16 + fr;
;                 const float rs = rsv[ai][m];
; #pragma unroll
;                 for (int bj = 0; bj < 2; ++bj) {
;                     const int cb = u.pn * BM + bj * HALF + wc * 32;
;                     f32x4 x1 = acc[ai][bj][m][0] * rs, x2 = acc[ai][bj][m][1] * rs;
;                     if ((cb % 96) == 64) { const f32x4 c = rc[ai][m], sn = rsn[ai][m]; const f32x4 y1 = x1 * c - x2 * sn, y2 = x1 * sn + x2 * c; x1 = y1; x2 = y2; }
;                     bf16_t* qp = Q + (size_t)row * 768 + cb + fq * 4; *(u32x2*)qp = pack4(x1); *(u32x2*)(qp + 16) = pack4(x2);
;                 }
	v_pk_fma_f32 v[66:67], v[60:61], v[152:153], v[66:67] neg_lo:[0,0,1] neg_hi:[0,0,1]
	v_pk_fma_f32 v[70:71], v[56:57], v[152:153], v[70:71]
	global_store_dwordx2 v[72:73], v[64:65], off offset:288
	v_pk_mul_f32 v[64:65], v[58:59], v[158:159]
	v_pk_mul_f32 v[68:69], v[62:63], v[158:159]
	v_cndmask_b32_e32 v60, v60, v66, vcc
	v_cndmask_b32_e32 v61, v61, v67, vcc
	v_cndmask_b32_e32 v66, v56, v70, vcc
	v_cndmask_b32_e32 v67, v57, v71, vcc
	v_mad_i64_i32 v[56:57], s[34:35], v196, s83, v[120:121]
	v_pk_fma_f32 v[64:65], v[62:63], v[154:155], v[64:65] neg_lo:[0,0,1] neg_hi:[0,0,1]
	v_pk_fma_f32 v[68:69], v[58:59], v[154:155], v[68:69]
	v_lshl_add_u64 v[56:57], v[56:57], 0, s[30:31]
	v_cndmask_b32_e32 v62, v62, v64, vcc
	v_cndmask_b32_e32 v63, v63, v65, vcc
	v_cndmask_b32_e32 v64, v58, v68, vcc
	v_cndmask_b32_e32 v65, v59, v69, vcc
	v_lshl_add_u64 v[56:57], v[56:57], 0, v[208:209]
	v_cvt_pk_bf16_f32 v58, v60, v61
	v_cvt_pk_bf16_f32 v59, v62, v63
	global_store_dwordx2 v[56:57], v[58:59], off
	v_cvt_pk_bf16_f32 v58, v66, v67
	v_cvt_pk_bf16_f32 v59, v64, v65
	v_pk_mul_f32 v[52:53], v[52:53], v[202:203] op_sel_hi:[1,0]
	v_pk_mul_f32 v[54:55], v[54:55], v[202:203] op_sel_hi:[1,0]
	v_pk_mul_f32 v[48:49], v[48:49], v[202:203] op_sel_hi:[1,0]
	v_pk_mul_f32 v[50:51], v[50:51], v[202:203] op_sel_hi:[1,0]
	global_store_dwordx2 v[56:57], v[58:59], off offset:32
	v_pk_mul_f32 v[58:59], v[50:51], v[158:159]
	v_pk_mul_f32 v[60:61], v[48:49], v[156:157]
	v_pk_mul_f32 v[62:63], v[54:55], v[158:159]
	v_pk_mul_f32 v[64:65], v[52:53], v[156:157]
	v_pk_fma_f32 v[60:61], v[52:53], v[152:153], v[60:61] neg_lo:[0,0,1] neg_hi:[0,0,1]
	v_pk_fma_f32 v[58:59], v[54:55], v[154:155], v[58:59] neg_lo:[0,0,1] neg_hi:[0,0,1]
	v_pk_fma_f32 v[64:65], v[48:49], v[152:153], v[64:65]
	v_pk_fma_f32 v[62:63], v[50:51], v[154:155], v[62:63]
	v_cndmask_b32_e64 v54, v54, v58, s[40:41]
	v_cndmask_b32_e64 v55, v55, v59, s[40:41]
	v_cndmask_b32_e64 v52, v52, v60, s[40:41]
	v_cndmask_b32_e64 v53, v53, v61, s[40:41]
	v_cndmask_b32_e64 v50, v50, v62, s[40:41]
	v_cndmask_b32_e64 v51, v51, v63, s[40:41]
	v_cndmask_b32_e64 v58, v48, v64, s[40:41]
	v_cndmask_b32_e64 v59, v49, v65, s[40:41]
	v_cvt_pk_bf16_f32 v48, v52, v53
	v_cvt_pk_bf16_f32 v49, v54, v55
	v_pk_mul_f32 v[44:45], v[44:45], v[198:199] op_sel_hi:[1,0]
	v_pk_mul_f32 v[40:41], v[40:41], v[198:199] op_sel_hi:[1,0]
	global_store_dwordx2 v[56:57], v[48:49], off offset:256
	v_cvt_pk_bf16_f32 v48, v58, v59
	v_cvt_pk_bf16_f32 v49, v50, v51
	v_pk_mul_f32 v[50:51], v[40:41], v[148:149]
	v_pk_mul_f32 v[54:55], v[44:45], v[148:149]
	v_pk_mul_f32 v[46:47], v[46:47], v[198:199] op_sel_hi:[1,0]
	v_pk_mul_f32 v[42:43], v[42:43], v[198:199] op_sel_hi:[1,0]
	v_pk_fma_f32 v[50:51], v[44:45], v[144:145], v[50:51] neg_lo:[0,0,1] neg_hi:[0,0,1]
	v_pk_fma_f32 v[54:55], v[40:41], v[144:145], v[54:55]
	global_store_dwordx2 v[56:57], v[48:49], off offset:288
	v_pk_mul_f32 v[48:49], v[42:43], v[150:151]
	v_pk_mul_f32 v[52:53], v[46:47], v[150:151]
	v_cndmask_b32_e32 v44, v44, v50, vcc
	v_cndmask_b32_e32 v45, v45, v51, vcc
	v_cndmask_b32_e32 v50, v40, v54, vcc
	v_cndmask_b32_e32 v51, v41, v55, vcc
	v_mad_i64_i32 v[40:41], s[34:35], v192, s83, v[120:121]
	v_pk_fma_f32 v[48:49], v[46:47], v[146:147], v[48:49] neg_lo:[0,0,1] neg_hi:[0,0,1]
	v_pk_fma_f32 v[52:53], v[42:43], v[146:147], v[52:53]
	v_lshl_add_u64 v[40:41], v[40:41], 0, s[30:31]
	v_cndmask_b32_e32 v46, v46, v48, vcc
	v_cndmask_b32_e32 v47, v47, v49, vcc
	v_cndmask_b32_e32 v48, v42, v52, vcc
	v_cndmask_b32_e32 v49, v43, v53, vcc
	v_lshl_add_u64 v[40:41], v[40:41], 0, v[208:209]
	v_cvt_pk_bf16_f32 v42, v44, v45
	v_cvt_pk_bf16_f32 v43, v46, v47
	global_store_dwordx2 v[40:41], v[42:43], off
	v_cvt_pk_bf16_f32 v42, v50, v51
	v_cvt_pk_bf16_f32 v43, v48, v49
	v_pk_mul_f32 v[36:37], v[36:37], v[198:199] op_sel_hi:[1,0]
	v_pk_mul_f32 v[38:39], v[38:39], v[198:199] op_sel_hi:[1,0]
	v_pk_mul_f32 v[32:33], v[32:33], v[198:199] op_sel_hi:[1,0]
	v_pk_mul_f32 v[34:35], v[34:35], v[198:199] op_sel_hi:[1,0]
	global_store_dwordx2 v[40:41], v[42:43], off offset:32
	v_pk_mul_f32 v[42:43], v[34:35], v[150:151]
	v_pk_mul_f32 v[44:45], v[32:33], v[148:149]
	v_pk_mul_f32 v[46:47], v[38:39], v[150:151]
	v_pk_mul_f32 v[48:49], v[36:37], v[148:149]
	v_pk_fma_f32 v[44:45], v[36:37], v[144:145], v[44:45] neg_lo:[0,0,1] neg_hi:[0,0,1]
	v_pk_fma_f32 v[42:43], v[38:39], v[146:147], v[42:43] neg_lo:[0,0,1] neg_hi:[0,0,1]
	v_pk_fma_f32 v[48:49], v[32:33], v[144:145], v[48:49]
	v_pk_fma_f32 v[46:47], v[34:35], v[146:147], v[46:47]
	v_cndmask_b32_e64 v38, v38, v42, s[40:41]
	v_cndmask_b32_e64 v39, v39, v43, s[40:41]
	v_cndmask_b32_e64 v36, v36, v44, s[40:41]
	v_cndmask_b32_e64 v37, v37, v45, s[40:41]
	v_cndmask_b32_e64 v34, v34, v46, s[40:41]
	v_cndmask_b32_e64 v35, v35, v47, s[40:41]
	v_cndmask_b32_e64 v42, v32, v48, s[40:41]
	v_cndmask_b32_e64 v43, v33, v49, s[40:41]
	v_cvt_pk_bf16_f32 v32, v36, v37
	v_cvt_pk_bf16_f32 v33, v38, v39
	v_pk_mul_f32 v[28:29], v[28:29], v[194:195] op_sel_hi:[1,0]
	v_pk_mul_f32 v[24:25], v[24:25], v[194:195] op_sel_hi:[1,0]
	global_store_dwordx2 v[40:41], v[32:33], off offset:256
	v_cvt_pk_bf16_f32 v32, v42, v43
	v_cvt_pk_bf16_f32 v33, v34, v35
	v_pk_mul_f32 v[34:35], v[24:25], v[140:141]
	v_pk_mul_f32 v[38:39], v[28:29], v[140:141]
	v_pk_mul_f32 v[30:31], v[30:31], v[194:195] op_sel_hi:[1,0]
; __device__ __forceinline__ u32x2 pack4(const f32x4 v) { u32x2 w; w.x = cvt_pk_bf16(v[0], v[1]); w.y = cvt_pk_bf16(v[2], v[3]); return w; }
; #define PG8_BAR __builtin_amdgcn_s_barrier()
;     __device__ __forceinline__ void operator()(const f32x4 (&acc)[2][2][4][2], const Unit& u, int wr, int wc, int fr, int fq) const {
;     ...
;                 const int row = u.pm * BM + ai * HALF + wr * 64 + m * 16 + fr;
;                 const float rs = rsv[ai][m];
; #pragma unroll
;                 for (int bj = 0; bj < 2; ++bj) {
;                     const int cb = u.pn * BM + bj * HALF + wc * 32;
;                     f32x4 x1 = acc[ai][bj][m][0] * rs, x2 = acc[ai][bj][m][1] * rs;
;                     if ((cb % 96) == 64) { const f32x4 c = rc[ai][m], sn = rsn[ai][m]; const f32x4 y1 = x1 * c - x2 * sn, y2 = x1 * sn + x2 * c; x1 = y1; x2 = y2; }
;                     bf16_t* qp = Q + (size_t)row * 768 + cb + fq * 4; *(u32x2*)qp = pack4(x1); *(u32x2*)(qp + 16) = pack4(x2);
;                 }
; template <class Epi, class Sched, bool ALIGN_EPI = false, bool SP2 = false>
; __device__ __forceinline__ void gemm_phase(PG8_LAS unsigned char* lds, const Gemm g, const Sched& S, const Epi& E) {
;     ...
;         if (!has_next) break;
; #pragma unroll
;         for (int a = 0; a < 2; ++a)
; #pragma unroll
;             for (int b = 0; b < 2; ++b)
; #pragma unroll
;                 for (int m = 0; m < 4; ++m)
; #pragma unroll
;                     for (int n = 0; n < 2; ++n) acc[a][b][m][n] = (f32x4){0.f, 0.f, 0.f, 0.f};
;         cur = nxt; cA = nA; cB = nB; ++ui;
;         if constexpr (ALIGN_EPI) { if (wr == 1) PG8_BAR; }
	v_pk_mul_f32 v[26:27], v[26:27], v[194:195] op_sel_hi:[1,0]
	v_pk_fma_f32 v[34:35], v[28:29], v[136:137], v[34:35] neg_lo:[0,0,1] neg_hi:[0,0,1]
	v_pk_fma_f32 v[38:39], v[24:25], v[136:137], v[38:39]
	global_store_dwordx2 v[40:41], v[32:33], off offset:288
	v_pk_mul_f32 v[32:33], v[26:27], v[142:143]
	v_pk_mul_f32 v[36:37], v[30:31], v[142:143]
	v_cndmask_b32_e32 v28, v28, v34, vcc
	v_cndmask_b32_e32 v29, v29, v35, vcc
	v_cndmask_b32_e32 v34, v24, v38, vcc
	v_cndmask_b32_e32 v35, v25, v39, vcc
	v_mad_i64_i32 v[24:25], s[34:35], v188, s83, v[120:121]
	v_pk_fma_f32 v[32:33], v[30:31], v[138:139], v[32:33] neg_lo:[0,0,1] neg_hi:[0,0,1]
	v_pk_fma_f32 v[36:37], v[26:27], v[138:139], v[36:37]
	v_lshl_add_u64 v[24:25], v[24:25], 0, s[30:31]
	v_cndmask_b32_e32 v30, v30, v32, vcc
	v_cndmask_b32_e32 v31, v31, v33, vcc
	v_cndmask_b32_e32 v32, v26, v36, vcc
	v_cndmask_b32_e32 v33, v27, v37, vcc
	v_lshl_add_u64 v[24:25], v[24:25], 0, v[208:209]
	v_cvt_pk_bf16_f32 v26, v28, v29
	v_cvt_pk_bf16_f32 v27, v30, v31
	global_store_dwordx2 v[24:25], v[26:27], off
	v_cvt_pk_bf16_f32 v26, v34, v35
	v_cvt_pk_bf16_f32 v27, v32, v33
	v_pk_mul_f32 v[20:21], v[20:21], v[194:195] op_sel_hi:[1,0]
	v_pk_mul_f32 v[22:23], v[22:23], v[194:195] op_sel_hi:[1,0]
	v_pk_mul_f32 v[16:17], v[16:17], v[194:195] op_sel_hi:[1,0]
	v_pk_mul_f32 v[18:19], v[18:19], v[194:195] op_sel_hi:[1,0]
	global_store_dwordx2 v[24:25], v[26:27], off offset:32
	v_pk_mul_f32 v[26:27], v[18:19], v[142:143]
	v_pk_mul_f32 v[28:29], v[16:17], v[140:141]
	v_pk_mul_f32 v[30:31], v[22:23], v[142:143]
	v_pk_mul_f32 v[32:33], v[20:21], v[140:141]
	v_pk_fma_f32 v[28:29], v[20:21], v[136:137], v[28:29] neg_lo:[0,0,1] neg_hi:[0,0,1]
	v_pk_fma_f32 v[26:27], v[22:23], v[138:139], v[26:27] neg_lo:[0,0,1] neg_hi:[0,0,1]
	v_pk_fma_f32 v[32:33], v[16:17], v[136:137], v[32:33]
	v_pk_fma_f32 v[30:31], v[18:19], v[138:139], v[30:31]
	v_cndmask_b32_e64 v22, v22, v26, s[40:41]
	v_cndmask_b32_e64 v23, v23, v27, s[40:41]
	v_cndmask_b32_e64 v20, v20, v28, s[40:41]
	v_cndmask_b32_e64 v21, v21, v29, s[40:41]
	v_cndmask_b32_e64 v18, v18, v30, s[40:41]
	v_cndmask_b32_e64 v19, v19, v31, s[40:41]
	v_cndmask_b32_e64 v26, v16, v32, s[40:41]
	v_cndmask_b32_e64 v27, v17, v33, s[40:41]
	v_cvt_pk_bf16_f32 v16, v20, v21
	v_cvt_pk_bf16_f32 v17, v22, v23
	v_pk_mul_f32 v[12:13], v[12:13], v[190:191] op_sel_hi:[1,0]
	v_pk_mul_f32 v[8:9], v[8:9], v[190:191] op_sel_hi:[1,0]
	global_store_dwordx2 v[24:25], v[16:17], off offset:256
	v_cvt_pk_bf16_f32 v16, v26, v27
	v_cvt_pk_bf16_f32 v17, v18, v19
	v_pk_mul_f32 v[18:19], v[8:9], v[132:133]
	v_pk_mul_f32 v[22:23], v[12:13], v[132:133]
	v_pk_mul_f32 v[14:15], v[14:15], v[190:191] op_sel_hi:[1,0]
	v_pk_mul_f32 v[10:11], v[10:11], v[190:191] op_sel_hi:[1,0]
	v_pk_fma_f32 v[18:19], v[12:13], v[128:129], v[18:19] neg_lo:[0,0,1] neg_hi:[0,0,1]
	v_pk_fma_f32 v[22:23], v[8:9], v[128:129], v[22:23]
	global_store_dwordx2 v[24:25], v[16:17], off offset:288
	v_pk_mul_f32 v[16:17], v[10:11], v[134:135]
	v_pk_mul_f32 v[20:21], v[14:15], v[134:135]
	v_cndmask_b32_e32 v12, v12, v18, vcc
	v_cndmask_b32_e32 v13, v13, v19, vcc
	v_cndmask_b32_e32 v18, v8, v22, vcc
	v_cndmask_b32_e32 v19, v9, v23, vcc
	v_mad_i64_i32 v[8:9], s[34:35], v186, s83, v[120:121]
	v_pk_fma_f32 v[16:17], v[14:15], v[130:131], v[16:17] neg_lo:[0,0,1] neg_hi:[0,0,1]
	v_pk_fma_f32 v[20:21], v[10:11], v[130:131], v[20:21]
	v_lshl_add_u64 v[8:9], v[8:9], 0, s[30:31]
	v_cndmask_b32_e32 v14, v14, v16, vcc
	v_cndmask_b32_e32 v15, v15, v17, vcc
	v_cndmask_b32_e32 v16, v10, v20, vcc
	v_cndmask_b32_e32 v17, v11, v21, vcc
	v_lshl_add_u64 v[8:9], v[8:9], 0, v[208:209]
	v_cvt_pk_bf16_f32 v10, v12, v13
	v_cvt_pk_bf16_f32 v11, v14, v15
	global_store_dwordx2 v[8:9], v[10:11], off
	v_cvt_pk_bf16_f32 v10, v18, v19
	v_cvt_pk_bf16_f32 v11, v16, v17
	v_pk_mul_f32 v[4:5], v[4:5], v[190:191] op_sel_hi:[1,0]
	v_pk_mul_f32 v[0:1], v[0:1], v[190:191] op_sel_hi:[1,0]
	v_pk_mul_f32 v[2:3], v[2:3], v[190:191] op_sel_hi:[1,0]
	global_store_dwordx2 v[8:9], v[10:11], off offset:32
	v_pk_mul_f32 v[6:7], v[6:7], v[190:191] op_sel_hi:[1,0]
	v_pk_mul_f32 v[10:11], v[2:3], v[134:135]
	v_pk_mul_f32 v[12:13], v[0:1], v[132:133]
	v_pk_mul_f32 v[16:17], v[4:5], v[132:133]
	v_pk_fma_f32 v[12:13], v[4:5], v[128:129], v[12:13] neg_lo:[0,0,1] neg_hi:[0,0,1]
	v_pk_fma_f32 v[10:11], v[6:7], v[130:131], v[10:11] neg_lo:[0,0,1] neg_hi:[0,0,1]
	v_pk_mul_f32 v[14:15], v[6:7], v[134:135]
	v_pk_fma_f32 v[16:17], v[0:1], v[128:129], v[16:17]
	v_pk_fma_f32 v[14:15], v[2:3], v[130:131], v[14:15]
	v_cndmask_b32_e64 v6, v6, v10, s[40:41]
	v_cndmask_b32_e64 v7, v7, v11, s[40:41]
	v_cndmask_b32_e64 v4, v4, v12, s[40:41]
	v_cndmask_b32_e64 v5, v5, v13, s[40:41]
	v_cndmask_b32_e64 v10, v0, v16, s[40:41]
	v_cndmask_b32_e64 v11, v1, v17, s[40:41]
	v_cvt_pk_bf16_f32 v0, v4, v5
	v_cvt_pk_bf16_f32 v1, v6, v7
	s_and_b64 vcc, exec, s[38:39]
	s_mov_b64 s[30:31], -1
	v_cndmask_b32_e64 v2, v2, v14, s[40:41]
	v_cndmask_b32_e64 v3, v3, v15, s[40:41]
	global_store_dwordx2 v[8:9], v[0:1], off offset:256
	v_cvt_pk_bf16_f32 v0, v10, v11
	v_cvt_pk_bf16_f32 v1, v2, v3
	global_store_dwordx2 v[8:9], v[0:1], off offset:288
	s_cbranch_vccnz .LBB0_1138
	s_mov_b32 s82, 0
	s_andn2_b64 vcc, exec, s[28:29]
	s_cbranch_vccnz .LBB0_1137
	s_mov_b32 s82, 1
	s_branch .LBB0_1137

; __device__ __forceinline__ int opaque_tid() { int t = threadIdx.x; asm volatile("" : "+v"(t)); return t; }
; #define PG8_STAGE(bufoff, gbase, voff) do { _Pragma("unroll") for (int _i = 0; _i < 2; ++_i) \
;         __builtin_amdgcn_global_load_lds((const unsigned*)((const char*)(gbase) + (voff)[_i]), (PG8_LAS unsigned*)(lds + (bufoff) + ldsw + _i * 8192), 16, 0, 0); } while (0)
; #define PG8_WAIT_V(n) asm volatile("s_waitcnt vmcnt(" #n ")" ::: "memory")
; #define PG8_BAR __builtin_amdgcn_s_barrier()
; template <class Epi, class Sched, bool ALIGN_EPI = false, bool SP2 = false>
; __device__ __forceinline__ void gemm_phase(PG8_LAS unsigned char* lds, const Gemm g, const Sched& S, const Epi& E) {
;     const int tid = opaque_tid(), wid = __builtin_amdgcn_readfirstlane(tid >> 6), lane = tid & 63, wr = wid >> 2, wc = wid & 3, fr = lane & 15, fq = lane >> 4;
;     const int K = g.K, nt = K / BK;
;     unsigned voffA[2], voffB[2];
; #pragma unroll
;     for (int i = 0; i < 2; ++i) { int R, C; stage_rc(tid * 16 + i * 8192, R, C); const int Rb = Epi::PERM ? ((R & ~31) + perm32(R & 31)) : R;
;         voffA[i] = (unsigned)(R * K + C) * 2u; voffB[i] = (unsigned)(Rb * K + C) * 2u; }
;     const size_t kstep = (size_t)(BK * 2);
;     const size_t hstep = (size_t)HALF * K * 2;
;     const size_t tstep = 2 * hstep;
;     const unsigned ldsw = (unsigned)wid * 1024u;
;     const int aoff = lds_byte(wr * 64 + fr, fq * 8), boff = lds_byte(wc * 32 + fr, fq * 8);
;     ...
;         PG8_STAGE(PG8_SB(0, 0), cB, voffB); PG8_STAGE(PG8_SB(0, 1), cB + hstep, voffB); PG8_STAGE(PG8_SA(0, 0), cA, voffA); PG8_STAGE(PG8_SA(0, 1), cA + hstep, voffA);
;         if (wr == 1) PG8_BAR;
;         PG8_WAIT_V(2); PG8_BAR;
;         PG8_STAGE(PG8_SB(1, 0), cB + kstep, voffB); PG8_STAGE(PG8_SA(1, 0), cA + kstep, voffA); PG8_STAGE(PG8_SB(1, 1), cB + hstep + kstep, voffB);
;         PG8_WAIT_V(6); PG8_BAR;
.LBB0_1159:
	s_add_i32 m0, s8, 0x18000
	v_lshl_add_u64 v[0:1], v[0:1], 0, s[20:21]
	s_waitcnt vmcnt(2)
	s_barrier
	global_load_lds_dwordx4 v[0:1], off
	v_lshl_add_u64 v[0:1], v[2:3], 0, s[20:21]
	s_add_i32 m0, s8, 0x1a000
	s_add_i32 s60, s8, 0x8000
	global_load_lds_dwordx4 v[0:1], off
	v_lshl_add_u64 v[0:1], v[8:9], 0, s[20:21]
	s_mov_b32 m0, s60
	s_add_i32 s61, s8, 0xa000
	global_load_lds_dwordx4 v[0:1], off
	v_lshl_add_u64 v[0:1], v[10:11], 0, s[20:21]
	s_mov_b32 m0, s61
	v_bfe_u32 v13, v12, 4, 2
	global_load_lds_dwordx4 v[0:1], off
	s_add_i32 m0, s8, 0x1c000
	v_lshl_add_u64 v[0:1], v[4:5], 0, s[20:21]
	global_load_lds_dwordx4 v[0:1], off
	v_lshl_add_u64 v[0:1], v[6:7], 0, s[20:21]
	s_add_i32 m0, s8, 0x1e000
	s_lshr_b32 s1, s1, 26
	global_load_lds_dwordx4 v[0:1], off
	v_and_b32_e32 v14, 15, v12
	s_add_i32 s1, s0, s1
	v_lshlrev_b32_e32 v15, 4, v13
	v_lshlrev_b32_e32 v12, 2, v12
	s_and_b32 s28, s28, 3
	s_ashr_i32 s48, s1, 6
	v_lshl_or_b32 v165, s29, 6, v14
	v_lshl_or_b32 v14, v14, 6, v15
	s_lshl_b32 s1, s29, 13
	v_and_b32_e32 v12, 32, v12
	v_bitop3_b32 v15, v14, s1, v12 bitop3:0xde
	s_lshl_b32 s59, s28, 5
	s_lshl_b32 s1, s28, 12
	s_cmp_gt_i32 s0, 63
	s_cselect_b64 s[52:53], -1, 0
	s_add_i32 s62, s48, -2
	s_cmpk_lt_u32 s27, 0x100
	s_cselect_b64 s[54:55], -1, 0
	s_cmp_gt_u32 s28, 1
	s_cselect_b64 s[56:57], -1, 0
	s_lshl_b32 s64, s38, 3
	s_abs_i32 s66, s64
	v_cvt_f32_u32_e32 v0, s66
	v_bitop3_b32 v190, v14, s1, v12 bitop3:0xde
	s_sub_i32 s0, 0, s66
	s_waitcnt vmcnt(6)
	v_rcp_iflag_f32_e32 v0, v0
	v_lshlrev_b32_e32 v164, 2, v13
	s_ashr_i32 s27, s26, 31
	s_lshl_b32 s63, s38, 4
	v_mul_f32_e32 v0, 0x4f7ffffe, v0
	v_cvt_u32_f32_e32 v0, v0
	s_bfe_i32 s65, s38, 0x1001c
	s_mov_b32 s67, 0
	v_lshl_add_u64 v[166:167], s[42:43], 0, v[160:161]
	v_readfirstlane_b32 s1, v0
	s_mul_i32 s0, s0, s1
	s_mul_hi_u32 s0, s1, s0
	s_add_i32 s68, s1, s0
	v_lshl_add_u64 v[168:169], s[42:43], 0, v[162:163]
	v_add_u32_e32 v191, 0, v15
	s_barrier
	s_mov_b32 s82, 0
	s_branch .LBB0_1162

; #define PG8_BAR __builtin_amdgcn_s_barrier()
; template <class Epi, class Sched, bool ALIGN_EPI = false, bool SP2 = false>
; __device__ __forceinline__ void gemm_phase(PG8_LAS unsigned char* lds, const Gemm g, const Sched& S, const Epi& E) {
;     ...
;         if constexpr (ALIGN_EPI) { if (wr == 1) PG8_BAR; }
.LBB0_1168:
	s_cmp_eq_u32 s82, 1
	s_cbranch_scc0 .Lno_restore_bar_6
	s_barrier

; __device__ __forceinline__ u32x2 pack4(const f32x4 v) { u32x2 w; w.x = cvt_pk_bf16(v[0], v[1]); w.y = cvt_pk_bf16(v[2], v[3]); return w; }
; #define PG8_BAR __builtin_amdgcn_s_barrier()
;     __device__ __forceinline__ void operator()(const f32x4 (&acc)[2][2][4][2], const Unit& u, int wr, int wc, int fr, int fq) const {
;     ...
;                     const int cb = u.pn * BM + bj * HALF + wc * 32, h = cb >> 7, w = cb & 127;
;                     bf16_t* p = (w < 64) ? (KM + (size_t)row * 768 + h * 96 + w + fq * 4) : (VM + (size_t)row * 512 + h * 64 + (w - 64) + fq * 4);
;                     *(u32x2*)p = pack4(acc[ai][bj][m][0] * rs); *(u32x2*)(p + 16) = pack4(acc[ai][bj][m][1] * rs);
; template <class Epi, class Sched, bool ALIGN_EPI = false, bool SP2 = false>
; __device__ __forceinline__ void gemm_phase(PG8_LAS unsigned char* lds, const Gemm g, const Sched& S, const Epi& E) {
;     ...
;         if (!has_next) break;
; #pragma unroll
;         for (int a = 0; a < 2; ++a)
; #pragma unroll
;             for (int b = 0; b < 2; ++b)
; #pragma unroll
;                 for (int m = 0; m < 4; ++m)
; #pragma unroll
;                     for (int n = 0; n < 2; ++n) acc[a][b][m][n] = (f32x4){0.f, 0.f, 0.f, 0.f};
;         cur = nxt; cA = nA; cB = nB; ++ui;
;         if constexpr (ALIGN_EPI) { if (wr == 1) PG8_BAR; }
.LBB0_1237:
	v_mov_b32_e32 v17, v16
	v_lshl_add_u64 v[8:9], v[8:9], 0, v[208:209]
	v_mov_b32_e32 v10, v16
	v_mov_b32_e32 v11, v16
	v_pk_mul_f32 v[4:5], v[4:5], v[16:17]
	v_pk_mul_f32 v[0:1], v[0:1], v[16:17]
	s_and_b64 vcc, exec, s[38:39]
	s_mov_b64 s[30:31], -1
	v_pk_mul_f32 v[6:7], v[6:7], v[10:11]
	v_cvt_pk_bf16_f32 v4, v4, v5
	v_pk_mul_f32 v[2:3], v[2:3], v[10:11]
	v_cvt_pk_bf16_f32 v5, v6, v7
	global_store_dwordx2 v[8:9], v[4:5], off
	v_cvt_pk_bf16_f32 v0, v0, v1
	v_cvt_pk_bf16_f32 v1, v2, v3
	global_store_dwordx2 v[8:9], v[0:1], off offset:32
	s_cbranch_vccnz .LBB0_1161
	s_mov_b32 s82, 0
	s_andn2_b64 vcc, exec, s[50:51]
	s_cbranch_vccnz .LBB0_1160
	s_mov_b32 s82, 1
	s_branch .LBB0_1160

; #define PG8_STAGE(bufoff, gbase, voff) do { _Pragma("unroll") for (int _i = 0; _i < 2; ++_i) \
;         __builtin_amdgcn_global_load_lds((const unsigned*)((const char*)(gbase) + (voff)[_i]), (PG8_LAS unsigned*)(lds + (bufoff) + ldsw + _i * 8192), 16, 0, 0); } while (0)
; #define PG8_WAIT_V(n) asm volatile("s_waitcnt vmcnt(" #n ")" ::: "memory")
; #define PG8_BAR __builtin_amdgcn_s_barrier()
;     __device__ __forceinline__ void operator()(const f32x4 (&acc)[2][2][4][2], const Unit& u, int wr, int wc, int fr, int fq) const {
;         float* wl = wlds + (wr * 4 + wc) * 576;
;         const int lane = fq * 16 + fr, rl = lane >> 3, ch = lane & 7;
;         f32x4 rb[2][2][2][2];
;         const size_t cbase = (size_t)u.pn * BM + wc * 32 + ch * 4;
; template <class Epi, class Sched, bool ALIGN_EPI = false, bool SP2 = false>
; __device__ __forceinline__ void gemm_phase(PG8_LAS unsigned char* lds, const Gemm g, const Sched& S, const Epi& E) {
;     ...
;         PG8_STAGE(PG8_SB(0, 0), cB, voffB); PG8_STAGE(PG8_SB(0, 1), cB + hstep, voffB); PG8_STAGE(PG8_SA(0, 0), cA, voffA); PG8_STAGE(PG8_SA(0, 1), cA + hstep, voffA);
;         if (wr == 1) PG8_BAR;
;         PG8_WAIT_V(2); PG8_BAR;
;         PG8_STAGE(PG8_SB(1, 0), cB + kstep, voffB); PG8_STAGE(PG8_SA(1, 0), cA + kstep, voffA); PG8_STAGE(PG8_SB(1, 1), cB + hstep + kstep, voffB);
;         PG8_WAIT_V(6); PG8_BAR;
.LBB0_1469:
	s_cmp_eq_u32 s3, 2
	s_cselect_b64 s[40:41], -1, 0
	s_add_i32 m0, s9, 0x18000
	v_lshl_add_u64 v[0:1], v[0:1], 0, s[20:21]
	s_waitcnt vmcnt(2)
	s_barrier
	global_load_lds_dwordx4 v[0:1], off
	v_lshl_add_u64 v[0:1], v[2:3], 0, s[20:21]
	s_add_i32 m0, s9, 0x1a000
	s_add_i32 s37, s9, 0x8000
	global_load_lds_dwordx4 v[0:1], off
	v_lshl_add_u64 v[0:1], v[8:9], 0, s[20:21]
	s_mov_b32 m0, s37
	s_add_i32 s48, s9, 0xa000
	global_load_lds_dwordx4 v[0:1], off
	v_lshl_add_u64 v[0:1], v[10:11], 0, s[20:21]
	s_mov_b32 m0, s48
	s_lshr_b32 s1, s1, 26
	global_load_lds_dwordx4 v[0:1], off
	s_add_i32 m0, s9, 0x1c000
	v_lshl_add_u64 v[0:1], v[4:5], 0, s[20:21]
	global_load_lds_dwordx4 v[0:1], off
	v_lshl_add_u64 v[0:1], v[6:7], 0, s[20:21]
	s_add_i32 m0, s9, 0x1e000
	s_add_i32 s1, s0, s1
	global_load_lds_dwordx4 v[0:1], off
	v_and_b32_e32 v0, 15, v12
	v_and_b32_e32 v1, 48, v12
	v_lshlrev_b32_e32 v3, 2, v12
	v_cndmask_b32_e64 v130, 1.0, 0, s[40:41]
	s_and_b32 s40, s38, 3
	s_ashr_i32 s58, s1, 6
	v_lshl_or_b32 v2, v0, 6, v1
	s_lshl_b32 s1, s39, 13
	v_and_b32_e32 v3, 32, v3
	v_bitop3_b32 v4, v2, s1, v3 bitop3:0xde
	s_lshl_b32 s1, s40, 12
	s_cmp_gt_i32 s0, 63
	s_cselect_b64 s[52:53], -1, 0
	s_add_i32 s59, s58, -2
	v_bitop3_b32 v133, v2, s1, v3 bitop3:0xde
	s_cmpk_lt_u32 s27, 0x100
	v_and_b32_e32 v3, 7, v12
	s_cselect_b64 s[54:55], -1, 0
	s_lshl_b32 s0, s39, 2
	v_lshlrev_b32_e32 v5, 2, v3
	s_or_b32 s0, s0, s40
	v_lshl_or_b32 v132, s40, 5, v5
	s_ashr_i32 s27, s26, 31
	s_lshl_b32 s1, s40, 2
	v_readlane_b32 s40, v252, 38
	v_readlane_b32 s41, v252, 39
	s_add_u32 s61, s40, s1
	s_addc_u32 s62, s41, 0
	s_lshl_b32 s64, s29, 3
	s_abs_i32 s65, s64
	v_cvt_f32_u32_e32 v5, s65
	s_mulk_i32 s0, 0x900
	v_mul_u32_u24_e32 v0, 36, v0
	s_add_i32 s0, s0, 0
	s_add_i32 s0, s0, 0x20000
	v_lshlrev_b32_e32 v0, 2, v0
	v_add3_u32 v197, s0, v0, v1
	v_rcp_iflag_f32_e32 v1, v5
	v_bfe_u32 v2, v12, 3, 3
	v_lshl_or_b32 v196, s39, 6, v2
	v_mul_u32_u24_e32 v2, 36, v2
	v_mul_f32_e32 v1, 0x4f7ffffe, v1
	v_cvt_u32_f32_e32 v1, v1
	v_lshlrev_b32_e32 v0, 4, v3
	v_lshlrev_b32_e32 v2, 2, v2
	v_add3_u32 v198, s0, v0, v2
	s_sub_i32 s0, 0, s65
	v_readfirstlane_b32 s1, v1
	s_waitcnt vmcnt(6)
	s_mul_i32 s0, s0, s1
	s_mul_hi_u32 s0, s1, s0
	s_mov_b32 s60, 0
	v_cmp_eq_u32_e64 s[38:39], 0, v3
	s_lshl_b32 s63, s29, 4
	v_mov_b32_e32 v134, v130
	v_mov_b32_e32 v135, v130
	s_bfe_i32 s66, s29, 0x1001c
	s_add_i32 s67, s1, s0
	v_lshl_add_u64 v[136:137], s[42:43], 0, v[208:209]
	v_lshl_add_u64 v[138:139], s[42:43], 0, v[128:129]
	v_add_u32_e32 v199, 0, v4
	s_barrier
	s_mov_b32 s77, 0
	s_branch .LBB0_1472

; #define PG8_BAR __builtin_amdgcn_s_barrier()
; template <class Epi, class Sched, bool ALIGN_EPI = false, bool SP2 = false>
; __device__ __forceinline__ void gemm_phase(PG8_LAS unsigned char* lds, const Gemm g, const Sched& S, const Epi& E) {
;     ...
;         if constexpr (ALIGN_EPI) { if (wr == 1) PG8_BAR; }
.LBB0_1478:
	s_cmp_eq_u32 s77, 1
	s_cbranch_scc0 .Lno_restore_bar_7
	s_barrier

; #define PG8_BAR __builtin_amdgcn_s_barrier()
;     __device__ __forceinline__ void operator()(const f32x4 (&acc)[2][2][4][2], const Unit& u, int wr, int wc, int fr, int fq) const {
;     ...
;                 for (int i = 0; i < 2; ++i) { float t = sq[i]; t += dpp_f(t, 0); t += dpp_f(t, 1); t += dpp_f(t, 2);
;                     if (ch == 0) ss[(size_t)(row0 + 8 * i) * 16 + u.pn * 4 + wc] = t; }
; template <class Epi, class Sched, bool ALIGN_EPI = false, bool SP2 = false>
; __device__ __forceinline__ void gemm_phase(PG8_LAS unsigned char* lds, const Gemm g, const Sched& S, const Epi& E) {
;     ...
;         if (!has_next) break;
; #pragma unroll
;         for (int a = 0; a < 2; ++a)
; #pragma unroll
;             for (int b = 0; b < 2; ++b)
; #pragma unroll
;                 for (int m = 0; m < 4; ++m)
; #pragma unroll
;                     for (int n = 0; n < 2; ++n) acc[a][b][m][n] = (f32x4){0.f, 0.f, 0.f, 0.f};
;         cur = nxt; cA = nA; cB = nB; ++ui;
;         if constexpr (ALIGN_EPI) { if (wr == 1) PG8_BAR; }
.LBB0_1515:
	s_or_b64 exec, exec, s[30:31]
	s_and_b64 vcc, exec, s[40:41]
	s_mov_b64 s[28:29], -1
	s_cbranch_vccnz .LBB0_1471
	s_mov_b32 s77, 0
	s_andn2_b64 vcc, exec, s[50:51]
	s_cbranch_vccnz .LBB0_1470
	s_mov_b32 s77, 1
	s_branch .LBB0_1470
